# v41 + SwiGLU epilogues: row sum-of-squares loaded at the unit-loop header into dedicated VGPRs (no loads / no vmcnt wait in the epilogue), peeled DMA waits re-counted (vmcnt 24), prologue drained
# speedup vs baseline: 1.0015x; 1.0015x over previous
; #define PG8_STAGE(bufoff, gbase, voff) do { _Pragma("unroll") for (int _i = 0; _i < 2; ++_i) \
;         __builtin_amdgcn_global_load_lds((const unsigned*)((const char*)(gbase) + (voff)[_i]), (PG8_LAS unsigned*)(lds + (bufoff) + ldsw + _i * 8192), 16, 0, 0); } while (0)
; #define PG8_LDA(dst, b, h) do { _Pragma("unroll") for (int m = 0; m < 4; ++m) _Pragma("unroll") for (int k = 0; k < 2; ++k) dst[m][k] = *(const PG8_LAS bf16x8*)(lds + PG8_SA(b, h) + aoff + m * 2048 + k * 1024); } while (0)
; #define PG8_LDB(dst, b, h) do { _Pragma("unroll") for (int n = 0; n < 2; ++n) _Pragma("unroll") for (int k = 0; k < 2; ++k) dst[n][k] = *(const PG8_LAS bf16x8*)(lds + PG8_SB(b, h) + boff + n * 2048 + k * 1024); } while (0)
; #define PG8_WAIT_V(n) asm volatile("s_waitcnt vmcnt(" #n ")" ::: "memory")
; #define PG8_WAIT_L(n) asm volatile("s_waitcnt lgkmcnt(" #n ")" ::: "memory")
; #define PG8_BAR __builtin_amdgcn_s_barrier()
; #define PG8_SCHED __builtin_amdgcn_sched_barrier(0)
;     __device__ __forceinline__ void operator()(f32x4 (&acc)[2][2][4][2], const Unit& u, int wr, int wc, int fr, int fq) const {
;     ...
;         for (int ai = 0; ai < 2; ++ai)
; #pragma unroll
;             for (int m = 0; m < 4; ++m) sq[ai][m] = ssq[row0 + ai * HALF + m * 16];
; template <class Epi, class Sched, bool ALIGN_EPI = false, bool SP2 = false>
; __device__ __forceinline__ void gemm_phase(PG8_LAS unsigned char* lds, const Gemm g, const Sched& S, const Epi& E) {
;     ...
;         const bool has_next = S.next(ui + 1, nxt);
;         const char* nA = has_next ? (const char*)g.A + (size_t)nxt.pm * tstepA : cA; const char* nB = has_next ? (const char*)g.Bt + (size_t)nxt.pn * tstepB : cB;
;         for (int t = 0; t < nt; t += 2) {
;             const bool last = (t == nt - 2);
;             const char* a1 = cA + (size_t)(t + 1) * kstepA;
;             const char* a2 = last ? nA : cA + (size_t)(t + 2) * kstepA; const char* b2 = last ? nB : cB + (size_t)(t + 2) * kstep;
;             const char* a3 = a2 + kstepA; const char* b3 = b2 + kstep;
;             if (last && has_next) S.a_ready(nxt);
;             if constexpr (SP2) {
;             PG8_LDB(B0, 0, 0); PG8_LDB(B1, 0, 1); PG8_SCHED; PG8_LDA(At, 0, 0); PG8_STAGE(PG8_SA(1, 1), a1 + hstepA, voffA);
;             PG8_WAIT_V(8); PG8_WAIT_L(0); PG8_BAR; PG8_MMA(0, 0, At, B0); PG8_MMA(0, 1, At, B1); PG8_BAR; PG8_SCHED;
.LBB0_138:
	v_lshl_add_u32 v150, s68, 8, v142
	v_ashrrev_i32_e32 v151, 31, v150
	v_lshl_add_u64 v[150:151], v[150:151], 2, s[22:23]
	global_load_dword v247, v[150:151], off
	global_load_dword v248, v[150:151], off offset:64
	global_load_dword v249, v[150:151], off offset:128
	global_load_dword v250, v[150:151], off offset:192
	global_load_dword v251, v[150:151], off offset:512
	global_load_dword v252, v[150:151], off offset:576
	global_load_dword v253, v[150:151], off offset:640
	global_load_dword v254, v[150:151], off offset:704
	s_add_i32 s78, s78, 1
	s_mul_i32 s2, s78, s82
	s_mul_hi_u32 s3, s78, s85
	s_add_i32 s3, s3, s2
	s_mul_i32 s2, s78, s85
	s_add_u32 s60, s2, s16
	s_addc_u32 s61, s3, s15
	v_cmp_gt_i64_e32 vcc, s[60:61], v[140:141]
	v_cmp_lt_i64_e64 s[2:3], s[60:61], v[138:139]
	s_cbranch_vccnz .LBB0_140
	s_ashr_i32 s8, s60, 31
	s_lshr_b32 s8, s8, 29
	s_add_i32 s8, s60, s8
	s_ashr_i32 s9, s8, 3
	s_and_b32 s8, s8, -8
	s_sub_i32 s8, s60, s8
	s_cmp_lt_i32 s8, 0
	s_cselect_b32 s33, s17, 0x160
	s_mul_i32 s8, s8, s33
	s_add_i32 s8, s8, s9
	s_mul_hi_i32 s9, s8, 0x2e8ba2e9
	s_lshr_b32 s33, s9, 31
	s_ashr_i32 s9, s9, 4
	s_add_i32 s9, s9, s33
	s_lshl_b32 s33, s9, 2
	s_mulk_i32 s9, 0x58
	s_sub_i32 s8, s8, s9
	s_abs_i32 s9, s8
	s_ashr_i32 s56, s8, 2
	s_and_b32 s8, s8, 3
	s_add_i32 s58, s33, s8
.LBB0_140:
	s_ashr_i32 s59, s58, 31
	s_lshl_b64 s[60:61], s[58:59], 19
	s_add_u32 s60, s12, s60
	s_addc_u32 s61, s13, s61
	s_and_b64 s[62:63], s[2:3], exec
	s_cselect_b32 s59, s61, s71
	s_cselect_b32 s92, s60, s70
	s_ashr_i32 s57, s56, 31
	s_lshl_b64 s[62:63], s[56:57], 19
	s_add_u32 s62, s80, s62
	s_addc_u32 s63, s81, s63
	s_and_b64 s[94:95], s[2:3], exec
	s_cselect_b32 s57, s63, s73
	s_cselect_b32 s93, s62, s72
	s_add_u32 s70, s70, 0x10000
	s_addc_u32 s71, s71, 0
	s_add_u32 s72, s72, 0x10000
	s_addc_u32 s73, s73, 0
	s_mov_b32 s94, -2
	ds_read_b128 v[150:153], v143
	ds_read_b128 v[154:157], v143 offset:1024
	ds_read_b128 v[158:161], v143 offset:2048
	ds_read_b128 v[162:165], v143 offset:3072
	ds_read_b128 v[166:169], v144
	ds_read_b128 v[170:173], v144 offset:1024
	ds_read_b128 v[174:177], v144 offset:2048
	ds_read_b128 v[178:181], v144 offset:3072
	s_cmp_eq_u32 s94, 12
	s_cselect_b32 s97, s59, s71
	s_cselect_b32 s96, s92, s70
	s_cselect_b32 vcc_hi, s57, s73
	s_cselect_b32 vcc_lo, s93, s72
	s_movk_i32 s8, 0xc000
	v_lshl_add_u64 v[186:187], s[70:71], 0, v[128:129]
	s_mov_b32 s9, -1
	v_lshl_add_u64 v[220:221], v[186:187], 0, s[8:9]
	s_movk_i32 s8, 0xe000
	s_add_i32 m0, s18, 0xc000
	s_mov_b32 s9, -1
	ds_read_b128 v[182:185], v145
	ds_read_b128 v[190:193], v145 offset:1024
	ds_read_b128 v[194:197], v145 offset:2048
	ds_read_b128 v[198:201], v145 offset:3072
	ds_read_b128 v[202:205], v145 offset:4096
	ds_read_b128 v[206:209], v145 offset:5120
	ds_read_b128 v[210:213], v145 offset:6144
	ds_read_b128 v[214:217], v145 offset:7168
	global_load_lds_dwordx4 v[220:221], off
	v_lshl_add_u64 v[186:187], v[186:187], 0, s[8:9]
	s_add_i32 m0, s18, 0xe000
	s_nop 0
	global_load_lds_dwordx4 v[186:187], off
	s_waitcnt vmcnt(24)
	s_waitcnt lgkmcnt(0)
	s_barrier
	s_waitcnt lgkmcnt(0)
	v_mfma_f32_16x16x32_bf16 v[116:119], v[150:153], v[182:185], 0
	v_mfma_f32_16x16x32_bf16 v[112:115], v[158:161], v[182:185], 0
	v_mfma_f32_16x16x32_bf16 v[108:111], v[150:153], v[194:197], 0
	v_mfma_f32_16x16x32_bf16 v[100:103], v[158:161], v[194:197], 0
	v_mfma_f32_16x16x32_bf16 v[92:95], v[150:153], v[202:205], 0
	v_mfma_f32_16x16x32_bf16 v[84:87], v[158:161], v[202:205], 0
	v_mfma_f32_16x16x32_bf16 v[76:79], v[150:153], v[210:213], 0
	v_mfma_f32_16x16x32_bf16 v[68:71], v[158:161], v[210:213], 0
	v_mfma_f32_16x16x32_bf16 v[116:119], v[154:157], v[190:193], v[116:119]
	v_mfma_f32_16x16x32_bf16 v[112:115], v[162:165], v[190:193], v[112:115]
	v_mfma_f32_16x16x32_bf16 v[108:111], v[154:157], v[198:201], v[108:111]
	v_mfma_f32_16x16x32_bf16 v[100:103], v[162:165], v[198:201], v[100:103]
	v_mfma_f32_16x16x32_bf16 v[92:95], v[154:157], v[206:209], v[92:95]
	v_mfma_f32_16x16x32_bf16 v[84:87], v[162:165], v[206:209], v[84:87]
	v_mfma_f32_16x16x32_bf16 v[76:79], v[154:157], v[214:217], v[76:79]
	v_mfma_f32_16x16x32_bf16 v[68:71], v[162:165], v[214:217], v[68:71]
	v_mfma_f32_16x16x32_bf16 v[124:127], v[166:169], v[182:185], 0
	v_mfma_f32_16x16x32_bf16 v[120:123], v[174:177], v[182:185], 0
	v_mfma_f32_16x16x32_bf16 v[104:107], v[166:169], v[194:197], 0
	v_mfma_f32_16x16x32_bf16 v[96:99], v[174:177], v[194:197], 0
	v_mfma_f32_16x16x32_bf16 v[88:91], v[166:169], v[202:205], 0
	v_mfma_f32_16x16x32_bf16 v[80:83], v[174:177], v[202:205], 0
	v_mfma_f32_16x16x32_bf16 v[72:75], v[166:169], v[210:213], 0
	v_mfma_f32_16x16x32_bf16 v[64:67], v[174:177], v[210:213], 0
	v_mfma_f32_16x16x32_bf16 v[124:127], v[170:173], v[190:193], v[124:127]
	v_mfma_f32_16x16x32_bf16 v[120:123], v[178:181], v[190:193], v[120:123]
	v_mfma_f32_16x16x32_bf16 v[104:107], v[170:173], v[198:201], v[104:107]
	v_mfma_f32_16x16x32_bf16 v[96:99], v[178:181], v[198:201], v[96:99]
	v_mfma_f32_16x16x32_bf16 v[88:91], v[170:173], v[206:209], v[88:91]
	v_mfma_f32_16x16x32_bf16 v[80:83], v[178:181], v[206:209], v[80:83]
	v_mfma_f32_16x16x32_bf16 v[72:75], v[170:173], v[214:217], v[72:75]
	v_mfma_f32_16x16x32_bf16 v[64:67], v[178:181], v[214:217], v[64:67]
	s_barrier
; #define PG8_STAGE(bufoff, gbase, voff) do { _Pragma("unroll") for (int _i = 0; _i < 2; ++_i) \
;         __builtin_amdgcn_global_load_lds((const unsigned*)((const char*)(gbase) + (voff)[_i]), (PG8_LAS unsigned*)(lds + (bufoff) + ldsw + _i * 8192), 16, 0, 0); } while (0)
; #define PG8_LDA(dst, b, h) do { _Pragma("unroll") for (int m = 0; m < 4; ++m) _Pragma("unroll") for (int k = 0; k < 2; ++k) dst[m][k] = *(const PG8_LAS bf16x8*)(lds + PG8_SA(b, h) + aoff + m * 2048 + k * 1024); } while (0)
; #define PG8_LDB(dst, b, h) do { _Pragma("unroll") for (int n = 0; n < 2; ++n) _Pragma("unroll") for (int k = 0; k < 2; ++k) dst[n][k] = *(const PG8_LAS bf16x8*)(lds + PG8_SB(b, h) + boff + n * 2048 + k * 1024); } while (0)
; #define PG8_MMA(ai, bj, At, Bt) do { __builtin_amdgcn_s_setprio(1); _Pragma("unroll") for (int m = 0; m < 4; ++m) _Pragma("unroll") for (int n = 0; n < 2; ++n) _Pragma("unroll") for (int k = 0; k < 2; ++k) \
;         acc[ai][bj][m][n] = __builtin_amdgcn_mfma_f32_16x16x32_bf16(Bt[n][k], At[m][k], acc[ai][bj][m][n], 0, 0, 0); __builtin_amdgcn_s_setprio(0); } while (0)
; #define PG8_WAIT_V(n) asm volatile("s_waitcnt vmcnt(" #n ")" ::: "memory")
; #define PG8_WAIT_L(n) asm volatile("s_waitcnt lgkmcnt(" #n ")" ::: "memory")
; #define PG8_BAR __builtin_amdgcn_s_barrier()
; #define PG8_SCHED __builtin_amdgcn_sched_barrier(0)
; template <class Epi, class Sched, bool ALIGN_EPI = false, bool SP2 = false>
; __device__ __forceinline__ void gemm_phase(PG8_LAS unsigned char* lds, const Gemm g, const Sched& S, const Epi& E) {
;     ...
;             PG8_LDA(At, 0, 1); PG8_STAGE(PG8_SB(0, 0), b2, voffB); PG8_STAGE(PG8_SB(0, 1), b2 + hstepB, voffB); PG8_STAGE(PG8_SA(0, 0), a2, voffA);
;             PG8_WAIT_V(8); PG8_WAIT_L(0); PG8_BAR; PG8_MMA(1, 0, At, B0); PG8_MMA(1, 1, At, B1); PG8_BAR; PG8_SCHED;
;             PG8_LDB(B0, 1, 0); PG8_LDB(B1, 1, 1); PG8_SCHED; PG8_LDA(At, 1, 0); PG8_STAGE(PG8_SA(0, 1), a2 + hstepA, voffA);
	s_add_i32 s8, s86, s14
	v_lshl_add_u64 v[186:187], vcc, 0, v[128:129]
	s_mov_b32 m0, s8
	ds_read_b128 v[182:185], v145 offset:16384
	ds_read_b128 v[190:193], v145 offset:17408
	ds_read_b128 v[194:197], v145 offset:18432
	ds_read_b128 v[198:201], v145 offset:19456
	ds_read_b128 v[202:205], v145 offset:20480
	ds_read_b128 v[206:209], v145 offset:21504
	ds_read_b128 v[210:213], v145 offset:22528
	ds_read_b128 v[214:217], v145 offset:23552
	global_load_lds_dwordx4 v[186:187], off
	v_lshl_add_u64 v[220:221], v[186:187], 0, s[4:5]
	s_add_i32 m0, s8, 0x2000
	s_add_i32 s8, s89, s14
	global_load_lds_dwordx4 v[220:221], off
	v_lshl_add_u64 v[220:221], v[186:187], 0, s[6:7]
	s_mov_b32 m0, s8
	s_nop 0
	global_load_lds_dwordx4 v[220:221], off
	v_lshl_add_u64 v[220:221], v[186:187], 0, s[30:31]
	s_add_i32 m0, s8, 0x2000
	s_nop 0
	global_load_lds_dwordx4 v[220:221], off
	v_lshl_add_u64 v[220:221], s[96:97], 0, v[128:129]
	s_mov_b32 m0, s18
	v_lshl_add_u64 v[222:223], v[220:221], 0, s[4:5]
	global_load_lds_dwordx4 v[220:221], off
	s_mov_b32 m0, s19
	s_nop 0
	global_load_lds_dwordx4 v[222:223], off
	s_waitcnt vmcnt(24)
	s_waitcnt lgkmcnt(0)
	s_barrier
	s_waitcnt lgkmcnt(0)
	v_mfma_f32_16x16x32_bf16 v[60:63], v[150:153], v[182:185], 0
	v_mfma_f32_16x16x32_bf16 v[52:55], v[158:161], v[182:185], 0
	v_mfma_f32_16x16x32_bf16 v[44:47], v[150:153], v[194:197], 0
	v_mfma_f32_16x16x32_bf16 v[36:39], v[158:161], v[194:197], 0
	v_mfma_f32_16x16x32_bf16 v[28:31], v[150:153], v[202:205], 0
	v_mfma_f32_16x16x32_bf16 v[20:23], v[158:161], v[202:205], 0
	v_mfma_f32_16x16x32_bf16 v[12:15], v[150:153], v[210:213], 0
	v_mfma_f32_16x16x32_bf16 v[4:7], v[158:161], v[210:213], 0
	v_mfma_f32_16x16x32_bf16 v[60:63], v[154:157], v[190:193], v[60:63]
	v_mfma_f32_16x16x32_bf16 v[52:55], v[162:165], v[190:193], v[52:55]
	v_mfma_f32_16x16x32_bf16 v[44:47], v[154:157], v[198:201], v[44:47]
	v_mfma_f32_16x16x32_bf16 v[36:39], v[162:165], v[198:201], v[36:39]
	v_mfma_f32_16x16x32_bf16 v[28:31], v[154:157], v[206:209], v[28:31]
	v_mfma_f32_16x16x32_bf16 v[20:23], v[162:165], v[206:209], v[20:23]
	v_mfma_f32_16x16x32_bf16 v[12:15], v[154:157], v[214:217], v[12:15]
	v_mfma_f32_16x16x32_bf16 v[4:7], v[162:165], v[214:217], v[4:7]
	v_mfma_f32_16x16x32_bf16 v[56:59], v[166:169], v[182:185], 0
	v_mfma_f32_16x16x32_bf16 v[48:51], v[174:177], v[182:185], 0
	v_mfma_f32_16x16x32_bf16 v[40:43], v[166:169], v[194:197], 0
	v_mfma_f32_16x16x32_bf16 v[32:35], v[174:177], v[194:197], 0
	v_mfma_f32_16x16x32_bf16 v[24:27], v[166:169], v[202:205], 0
	v_mfma_f32_16x16x32_bf16 v[16:19], v[174:177], v[202:205], 0
	v_mfma_f32_16x16x32_bf16 v[8:11], v[166:169], v[210:213], 0
	v_mfma_f32_16x16x32_bf16 v[0:3], v[174:177], v[210:213], 0
	v_mfma_f32_16x16x32_bf16 v[56:59], v[170:173], v[190:193], v[56:59]
	v_mfma_f32_16x16x32_bf16 v[48:51], v[178:181], v[190:193], v[48:51]
	v_mfma_f32_16x16x32_bf16 v[40:43], v[170:173], v[198:201], v[40:43]
	v_mfma_f32_16x16x32_bf16 v[32:35], v[178:181], v[198:201], v[32:35]
	v_mfma_f32_16x16x32_bf16 v[24:27], v[170:173], v[206:209], v[24:27]
	v_mfma_f32_16x16x32_bf16 v[16:19], v[178:181], v[206:209], v[16:19]
	v_mfma_f32_16x16x32_bf16 v[8:11], v[170:173], v[214:217], v[8:11]
	v_mfma_f32_16x16x32_bf16 v[0:3], v[178:181], v[214:217], v[0:3]
	s_barrier
	ds_read_b128 v[150:153], v146
	ds_read_b128 v[154:157], v146 offset:1024
	ds_read_b128 v[158:161], v146 offset:2048
	ds_read_b128 v[162:165], v146 offset:3072
	ds_read_b128 v[166:169], v147
	ds_read_b128 v[170:173], v147 offset:1024
	ds_read_b128 v[174:177], v147 offset:2048
	ds_read_b128 v[178:181], v147 offset:3072
	s_mov_b32 m0, s74
	v_lshl_add_u64 v[222:223], v[220:221], 0, s[6:7]
	ds_read_b128 v[182:185], v145 offset:32768
	ds_read_b128 v[190:193], v145 offset:33792
	ds_read_b128 v[194:197], v145 offset:34816
	ds_read_b128 v[198:201], v145 offset:35840
	ds_read_b128 v[202:205], v145 offset:36864
	ds_read_b128 v[206:209], v145 offset:37888
	ds_read_b128 v[210:213], v145 offset:38912
	ds_read_b128 v[214:217], v145 offset:39936
	global_load_lds_dwordx4 v[222:223], off
	v_lshl_add_u64 v[222:223], v[220:221], 0, s[30:31]
	s_mov_b32 m0, s75
	s_nop 0
	global_load_lds_dwordx4 v[222:223], off
	s_waitcnt vmcnt(8)
	s_waitcnt lgkmcnt(0)
	s_barrier
; #define PG8_STAGE(bufoff, gbase, voff) do { _Pragma("unroll") for (int _i = 0; _i < 2; ++_i) \
;         __builtin_amdgcn_global_load_lds((const unsigned*)((const char*)(gbase) + (voff)[_i]), (PG8_LAS unsigned*)(lds + (bufoff) + ldsw + _i * 8192), 16, 0, 0); } while (0)
; #define PG8_LDA(dst, b, h) do { _Pragma("unroll") for (int m = 0; m < 4; ++m) _Pragma("unroll") for (int k = 0; k < 2; ++k) dst[m][k] = *(const PG8_LAS bf16x8*)(lds + PG8_SA(b, h) + aoff + m * 2048 + k * 1024); } while (0)
; #define PG8_MMA(ai, bj, At, Bt) do { __builtin_amdgcn_s_setprio(1); _Pragma("unroll") for (int m = 0; m < 4; ++m) _Pragma("unroll") for (int n = 0; n < 2; ++n) _Pragma("unroll") for (int k = 0; k < 2; ++k) \
;         acc[ai][bj][m][n] = __builtin_amdgcn_mfma_f32_16x16x32_bf16(Bt[n][k], At[m][k], acc[ai][bj][m][n], 0, 0, 0); __builtin_amdgcn_s_setprio(0); } while (0)
; #define PG8_WAIT_V(n) asm volatile("s_waitcnt vmcnt(" #n ")" ::: "memory")
; #define PG8_WAIT_L(n) asm volatile("s_waitcnt lgkmcnt(" #n ")" ::: "memory")
; #define PG8_BAR __builtin_amdgcn_s_barrier()
; #define PG8_SCHED __builtin_amdgcn_sched_barrier(0)
; template <class Epi, class Sched, bool ALIGN_EPI = false, bool SP2 = false>
; __device__ __forceinline__ void gemm_phase(PG8_LAS unsigned char* lds, const Gemm g, const Sched& S, const Epi& E) {
;     ...
;             PG8_WAIT_V(8); PG8_WAIT_L(0); PG8_BAR; PG8_MMA(0, 0, At, B0); PG8_MMA(0, 1, At, B1); PG8_BAR; PG8_SCHED;
;             PG8_LDA(At, 1, 1); PG8_STAGE(PG8_SB(1, 0), b3, voffB); PG8_STAGE(PG8_SB(1, 1), b3 + hstepB, voffB); PG8_STAGE(PG8_SA(1, 0), a3, voffA);
;             PG8_WAIT_V(8); PG8_WAIT_L(0); PG8_BAR; PG8_MMA(1, 0, At, B0); PG8_MMA(1, 1, At, B1); PG8_BAR; PG8_SCHED;
	s_waitcnt lgkmcnt(0)
	v_mfma_f32_16x16x32_bf16 v[116:119], v[150:153], v[182:185], v[116:119]
	v_mfma_f32_16x16x32_bf16 v[112:115], v[158:161], v[182:185], v[112:115]
	v_mfma_f32_16x16x32_bf16 v[108:111], v[150:153], v[194:197], v[108:111]
	v_mfma_f32_16x16x32_bf16 v[100:103], v[158:161], v[194:197], v[100:103]
	v_mfma_f32_16x16x32_bf16 v[92:95], v[150:153], v[202:205], v[92:95]
	v_mfma_f32_16x16x32_bf16 v[84:87], v[158:161], v[202:205], v[84:87]
	v_mfma_f32_16x16x32_bf16 v[76:79], v[150:153], v[210:213], v[76:79]
	v_mfma_f32_16x16x32_bf16 v[68:71], v[158:161], v[210:213], v[68:71]
	v_mfma_f32_16x16x32_bf16 v[116:119], v[154:157], v[190:193], v[116:119]
	v_mfma_f32_16x16x32_bf16 v[112:115], v[162:165], v[190:193], v[112:115]
	v_mfma_f32_16x16x32_bf16 v[108:111], v[154:157], v[198:201], v[108:111]
	v_mfma_f32_16x16x32_bf16 v[100:103], v[162:165], v[198:201], v[100:103]
	v_mfma_f32_16x16x32_bf16 v[92:95], v[154:157], v[206:209], v[92:95]
	v_mfma_f32_16x16x32_bf16 v[84:87], v[162:165], v[206:209], v[84:87]
	v_mfma_f32_16x16x32_bf16 v[76:79], v[154:157], v[214:217], v[76:79]
	v_mfma_f32_16x16x32_bf16 v[68:71], v[162:165], v[214:217], v[68:71]
	v_mfma_f32_16x16x32_bf16 v[124:127], v[166:169], v[182:185], v[124:127]
	v_mfma_f32_16x16x32_bf16 v[120:123], v[174:177], v[182:185], v[120:123]
	v_mfma_f32_16x16x32_bf16 v[104:107], v[166:169], v[194:197], v[104:107]
	v_mfma_f32_16x16x32_bf16 v[96:99], v[174:177], v[194:197], v[96:99]
	v_mfma_f32_16x16x32_bf16 v[88:91], v[166:169], v[202:205], v[88:91]
	v_mfma_f32_16x16x32_bf16 v[80:83], v[174:177], v[202:205], v[80:83]
	v_mfma_f32_16x16x32_bf16 v[72:75], v[166:169], v[210:213], v[72:75]
	v_mfma_f32_16x16x32_bf16 v[64:67], v[174:177], v[210:213], v[64:67]
	v_mfma_f32_16x16x32_bf16 v[124:127], v[170:173], v[190:193], v[124:127]
	v_mfma_f32_16x16x32_bf16 v[120:123], v[178:181], v[190:193], v[120:123]
	v_mfma_f32_16x16x32_bf16 v[104:107], v[170:173], v[198:201], v[104:107]
	v_mfma_f32_16x16x32_bf16 v[96:99], v[178:181], v[198:201], v[96:99]
	v_mfma_f32_16x16x32_bf16 v[88:91], v[170:173], v[206:209], v[88:91]
	v_mfma_f32_16x16x32_bf16 v[80:83], v[178:181], v[206:209], v[80:83]
	v_mfma_f32_16x16x32_bf16 v[72:75], v[170:173], v[214:217], v[72:75]
	v_mfma_f32_16x16x32_bf16 v[64:67], v[178:181], v[214:217], v[64:67]
	s_barrier
	s_add_i32 s8, s90, s14
	v_lshl_add_u64 v[222:223], v[186:187], 0, s[34:35]
	s_mov_b32 m0, s8
	ds_read_b128 v[182:185], v145 offset:49152
	ds_read_b128 v[190:193], v145 offset:50176
	ds_read_b128 v[194:197], v145 offset:51200
	ds_read_b128 v[198:201], v145 offset:52224
	ds_read_b128 v[202:205], v145 offset:53248
	ds_read_b128 v[206:209], v145 offset:54272
	ds_read_b128 v[210:213], v145 offset:55296
	ds_read_b128 v[214:217], v145 offset:56320
	global_load_lds_dwordx4 v[222:223], off
	v_lshl_add_u64 v[222:223], v[186:187], 0, s[36:37]
	s_add_i32 m0, s8, 0x2000
	s_add_i32 s8, s91, s14
	global_load_lds_dwordx4 v[222:223], off
	v_lshl_add_u64 v[222:223], v[186:187], 0, s[38:39]
	s_mov_b32 m0, s8
	v_lshl_add_u64 v[186:187], v[186:187], 0, s[40:41]
	global_load_lds_dwordx4 v[222:223], off
	s_add_i32 m0, s8, 0x2000
	s_nop 0
	global_load_lds_dwordx4 v[186:187], off
	v_lshl_add_u64 v[186:187], v[220:221], 0, s[34:35]
	s_mov_b32 m0, s76
	s_nop 0
	global_load_lds_dwordx4 v[186:187], off
	v_lshl_add_u64 v[186:187], v[220:221], 0, s[36:37]
	s_mov_b32 m0, s77
	s_nop 0
	global_load_lds_dwordx4 v[186:187], off
	s_waitcnt vmcnt(8)
	s_waitcnt lgkmcnt(0)
	s_barrier
	s_waitcnt lgkmcnt(0)
	v_mfma_f32_16x16x32_bf16 v[60:63], v[150:153], v[182:185], v[60:63]
	v_mfma_f32_16x16x32_bf16 v[52:55], v[158:161], v[182:185], v[52:55]
	v_mfma_f32_16x16x32_bf16 v[44:47], v[150:153], v[194:197], v[44:47]
	v_mfma_f32_16x16x32_bf16 v[36:39], v[158:161], v[194:197], v[36:39]
	v_mfma_f32_16x16x32_bf16 v[28:31], v[150:153], v[202:205], v[28:31]
	v_mfma_f32_16x16x32_bf16 v[20:23], v[158:161], v[202:205], v[20:23]
	v_mfma_f32_16x16x32_bf16 v[12:15], v[150:153], v[210:213], v[12:15]
	v_mfma_f32_16x16x32_bf16 v[4:7], v[158:161], v[210:213], v[4:7]
	v_mfma_f32_16x16x32_bf16 v[60:63], v[154:157], v[190:193], v[60:63]
	v_mfma_f32_16x16x32_bf16 v[52:55], v[162:165], v[190:193], v[52:55]
	v_mfma_f32_16x16x32_bf16 v[44:47], v[154:157], v[198:201], v[44:47]
	v_mfma_f32_16x16x32_bf16 v[36:39], v[162:165], v[198:201], v[36:39]
	v_mfma_f32_16x16x32_bf16 v[28:31], v[154:157], v[206:209], v[28:31]
	v_mfma_f32_16x16x32_bf16 v[20:23], v[162:165], v[206:209], v[20:23]
	v_mfma_f32_16x16x32_bf16 v[12:15], v[154:157], v[214:217], v[12:15]
	v_mfma_f32_16x16x32_bf16 v[4:7], v[162:165], v[214:217], v[4:7]
	v_mfma_f32_16x16x32_bf16 v[56:59], v[166:169], v[182:185], v[56:59]
	v_mfma_f32_16x16x32_bf16 v[48:51], v[174:177], v[182:185], v[48:51]
	v_mfma_f32_16x16x32_bf16 v[40:43], v[166:169], v[194:197], v[40:43]
	v_mfma_f32_16x16x32_bf16 v[32:35], v[174:177], v[194:197], v[32:35]
	v_mfma_f32_16x16x32_bf16 v[24:27], v[166:169], v[202:205], v[24:27]
	v_mfma_f32_16x16x32_bf16 v[16:19], v[174:177], v[202:205], v[16:19]
	v_mfma_f32_16x16x32_bf16 v[8:11], v[166:169], v[210:213], v[8:11]
	v_mfma_f32_16x16x32_bf16 v[0:3], v[174:177], v[210:213], v[0:3]
	v_mfma_f32_16x16x32_bf16 v[56:59], v[170:173], v[190:193], v[56:59]
	v_mfma_f32_16x16x32_bf16 v[48:51], v[178:181], v[190:193], v[48:51]
	v_mfma_f32_16x16x32_bf16 v[40:43], v[170:173], v[198:201], v[40:43]
	v_mfma_f32_16x16x32_bf16 v[32:35], v[178:181], v[198:201], v[32:35]
	v_mfma_f32_16x16x32_bf16 v[24:27], v[170:173], v[206:209], v[24:27]
	v_mfma_f32_16x16x32_bf16 v[16:19], v[178:181], v[206:209], v[16:19]
	v_mfma_f32_16x16x32_bf16 v[8:11], v[170:173], v[214:217], v[8:11]
	v_mfma_f32_16x16x32_bf16 v[0:3], v[178:181], v[214:217], v[0:3]
	s_barrier
	s_add_i32 s94, s94, 2
	s_add_u32 s70, s70, 0x10000
	s_addc_u32 s71, s71, 0
	s_add_u32 s72, s72, 0x10000
	s_addc_u32 s73, s73, 0
	s_cmp_gt_u32 s94, 13

; __device__ __forceinline__ unsigned cvt_pk_bf16(float lo, float hi) { unsigned r; asm volatile("v_cvt_pk_bf16_f32 %0, %1, %2" : "=v"(r) : "v"(lo), "v"(hi)); return r; }
;     __device__ __forceinline__ void operator()(f32x4 (&acc)[2][2][4][2], const Unit& u, int wr, int wc, int fr, int fq) const {
;         const int row0 = u.pm * BM + wr * 64 + fr, col0 = u.pn * HALF + wc * 32 + 8 * fq;
;         bf16_t* Ob = O + ((size_t)(u.pm * ldc + (col0 >> 6)) * BM) * 64;
;         float sq[2][4];
; #pragma unroll
;         for (int ai = 0; ai < 2; ++ai)
; #pragma unroll
;             for (int m = 0; m < 4; ++m) sq[ai][m] = ssq[row0 + ai * HALF + m * 16];
; #pragma unroll
;         for (int ai = 0; ai < 2; ++ai)
; #pragma unroll
;             for (int m = 0; m < 4; ++m) { const float ms = sq[ai][m] * (1.0f / 1024.0f) + 1e-6f, nrl = -__builtin_amdgcn_rsqf(ms) * LOG2E;
;                 float o[8];
; #pragma unroll
;                 for (int n = 0; n < 2; ++n)
; #pragma unroll
;                     for (int e = 0; e < 4; ++e) { const float a = acc[ai][0][m][n][e], bb = acc[ai][1][m][n][e];
;                         o[4 * n + e] = (a * bb) * __builtin_amdgcn_rcpf(__builtin_fmaf(__builtin_amdgcn_exp2f(a * nrl), ms, ms)); }
;                 u32x4 w; w.x = cvt_pk_bf16(o[0], o[1]); w.y = cvt_pk_bf16(o[2], o[3]); w.z = cvt_pk_bf16(o[4], o[5]); w.w = cvt_pk_bf16(o[6], o[7]);
;                 *(u32x4*)((char*)Ob + ai * HTB + lds_byte(wr * 64 + m * 16 + fr, (col0 & 63))) = w; }
.LBB0_144:
	s_lshl_b32 s8, s69, 7
	s_or_b32 s8, s8, s79
	s_mul_i32 s9, s68, 44
	s_ashr_i32 s8, s8, 6
	s_add_i32 s8, s8, s9
	s_ashr_i32 s9, s8, 31
	s_lshl_b64 s[8:9], s[8:9], 15
	s_add_u32 s68, s28, s8
	s_addc_u32 s69, s29, s9
	v_pk_mul_f32 v[124:125], v[116:117], v[124:125]
	v_pk_mul_f32 v[126:127], v[118:119], v[126:127]
	v_pk_mul_f32 v[120:121], v[112:113], v[120:121]
	v_pk_mul_f32 v[122:123], v[114:115], v[122:123]
	v_pk_mul_f32 v[104:105], v[108:109], v[104:105]
	v_pk_mul_f32 v[106:107], v[110:111], v[106:107]
	v_pk_mul_f32 v[96:97], v[100:101], v[96:97]
	v_pk_mul_f32 v[98:99], v[102:103], v[98:99]
	v_pk_mul_f32 v[88:89], v[92:93], v[88:89]
	v_pk_mul_f32 v[90:91], v[94:95], v[90:91]
	v_pk_mul_f32 v[80:81], v[84:85], v[80:81]
	v_pk_mul_f32 v[82:83], v[86:87], v[82:83]
	v_pk_mul_f32 v[72:73], v[76:77], v[72:73]
	v_pk_mul_f32 v[74:75], v[78:79], v[74:75]
	v_pk_mul_f32 v[64:65], v[68:69], v[64:65]
	v_pk_mul_f32 v[66:67], v[70:71], v[66:67]
	v_pk_mul_f32 v[56:57], v[60:61], v[56:57]
	v_pk_mul_f32 v[58:59], v[62:63], v[58:59]
	v_pk_mul_f32 v[48:49], v[52:53], v[48:49]
	v_pk_mul_f32 v[50:51], v[54:55], v[50:51]
	v_pk_mul_f32 v[40:41], v[44:45], v[40:41]
	v_pk_mul_f32 v[42:43], v[46:47], v[42:43]
	v_pk_mul_f32 v[32:33], v[36:37], v[32:33]
	v_pk_mul_f32 v[34:35], v[38:39], v[34:35]
	v_pk_mul_f32 v[24:25], v[28:29], v[24:25]
	v_pk_mul_f32 v[26:27], v[30:31], v[26:27]
	v_pk_mul_f32 v[16:17], v[20:21], v[16:17]
	v_pk_mul_f32 v[18:19], v[22:23], v[18:19]
	v_pk_mul_f32 v[8:9], v[12:13], v[8:9]
	v_pk_mul_f32 v[10:11], v[14:15], v[10:11]
	v_pk_mul_f32 v[0:1], v[4:5], v[0:1]
	v_pk_mul_f32 v[2:3], v[6:7], v[2:3]
	v_readlane_b32 s99, v246, 6
	s_nop 1
	s_cmp_lt_u32 s99, 4
	s_cbranch_scc0 .Lnoal_0
	s_barrier
.Lnoal_0:
	v_fmamk_f32 v154, v247, 0x3a800000, v148
	v_fmamk_f32 v162, v248, 0x3a800000, v148
	v_fmamk_f32 v164, v249, 0x3a800000, v148
	v_fmamk_f32 v166, v250, 0x3a800000, v148
	v_fmamk_f32 v168, v251, 0x3a800000, v148
	v_fmamk_f32 v170, v252, 0x3a800000, v148
	v_fmamk_f32 v172, v253, 0x3a800000, v148
	v_fmamk_f32 v174, v254, 0x3a800000, v148
	v_rsq_f32_e32 v155, v154
	v_rsq_f32_e32 v163, v162
	v_rsq_f32_e32 v165, v164
	v_rsq_f32_e32 v167, v166
	v_rsq_f32_e32 v169, v168
	v_rsq_f32_e32 v171, v170
	v_rsq_f32_e32 v173, v172
	v_rsq_f32_e32 v175, v174
	v_mul_f32_e32 v155, 0xbfb8aa3b, v155
	v_mul_f32_e32 v163, 0xbfb8aa3b, v163
	v_mul_f32_e32 v165, 0xbfb8aa3b, v165
	v_mul_f32_e32 v167, 0xbfb8aa3b, v167
	v_mul_f32_e32 v169, 0xbfb8aa3b, v169
	v_mul_f32_e32 v171, 0xbfb8aa3b, v171
	v_mul_f32_e32 v173, 0xbfb8aa3b, v173
	v_mul_f32_e32 v175, 0xbfb8aa3b, v175
	v_pk_mul_f32 v[116:117], v[116:117], v[154:155] op_sel:[0,1] op_sel_hi:[1,1]
	v_pk_mul_f32 v[118:119], v[118:119], v[154:155] op_sel:[0,1] op_sel_hi:[1,1]
	v_pk_mul_f32 v[112:113], v[112:113], v[154:155] op_sel:[0,1] op_sel_hi:[1,1]
	v_pk_mul_f32 v[114:115], v[114:115], v[154:155] op_sel:[0,1] op_sel_hi:[1,1]
	v_exp_f32_e32 v116, v116
	v_exp_f32_e32 v117, v117
	v_exp_f32_e32 v118, v118
	v_exp_f32_e32 v119, v119
	v_exp_f32_e32 v112, v112
	v_exp_f32_e32 v113, v113
	v_exp_f32_e32 v114, v114
	v_exp_f32_e32 v115, v115
	v_pk_fma_f32 v[116:117], v[116:117], v[154:155], v[154:155] op_sel_hi:[1,0,0]
	v_pk_fma_f32 v[118:119], v[118:119], v[154:155], v[154:155] op_sel_hi:[1,0,0]
	v_pk_fma_f32 v[112:113], v[112:113], v[154:155], v[154:155] op_sel_hi:[1,0,0]
	v_pk_fma_f32 v[114:115], v[114:115], v[154:155], v[154:155] op_sel_hi:[1,0,0]
	v_rcp_f32_e32 v116, v116
	v_rcp_f32_e32 v117, v117
	v_rcp_f32_e32 v118, v118
	v_rcp_f32_e32 v119, v119
	v_rcp_f32_e32 v112, v112
	v_rcp_f32_e32 v113, v113
	v_rcp_f32_e32 v114, v114
	v_rcp_f32_e32 v115, v115
	v_pk_mul_f32 v[124:125], v[124:125], v[116:117]
	v_pk_mul_f32 v[126:127], v[126:127], v[118:119]
	v_pk_mul_f32 v[120:121], v[120:121], v[112:113]
	v_pk_mul_f32 v[122:123], v[122:123], v[114:115]
	v_cvt_pk_bf16_f32 v208, v124, v125
	v_cvt_pk_bf16_f32 v209, v126, v127
	v_cvt_pk_bf16_f32 v210, v120, v121
	v_cvt_pk_bf16_f32 v211, v122, v123
	v_lshl_add_u64 v[176:177], s[68:69], 0, v[130:131]
	global_store_dwordx4 v[176:177], v[208:211], off sc1
	v_pk_mul_f32 v[108:109], v[108:109], v[162:163] op_sel:[0,1] op_sel_hi:[1,1]
	v_pk_mul_f32 v[110:111], v[110:111], v[162:163] op_sel:[0,1] op_sel_hi:[1,1]
	v_pk_mul_f32 v[100:101], v[100:101], v[162:163] op_sel:[0,1] op_sel_hi:[1,1]
	v_pk_mul_f32 v[102:103], v[102:103], v[162:163] op_sel:[0,1] op_sel_hi:[1,1]
	v_exp_f32_e32 v108, v108
	v_exp_f32_e32 v109, v109
	v_exp_f32_e32 v110, v110
	v_exp_f32_e32 v111, v111
	v_exp_f32_e32 v100, v100
	v_exp_f32_e32 v101, v101
	v_exp_f32_e32 v102, v102
	v_exp_f32_e32 v103, v103
	v_pk_fma_f32 v[108:109], v[108:109], v[162:163], v[162:163] op_sel_hi:[1,0,0]
	v_pk_fma_f32 v[110:111], v[110:111], v[162:163], v[162:163] op_sel_hi:[1,0,0]
	v_pk_fma_f32 v[100:101], v[100:101], v[162:163], v[162:163] op_sel_hi:[1,0,0]
	v_pk_fma_f32 v[102:103], v[102:103], v[162:163], v[162:163] op_sel_hi:[1,0,0]
	v_rcp_f32_e32 v108, v108
	v_rcp_f32_e32 v109, v109
	v_rcp_f32_e32 v110, v110
	v_rcp_f32_e32 v111, v111
	v_rcp_f32_e32 v100, v100
	v_rcp_f32_e32 v101, v101
	v_rcp_f32_e32 v102, v102
	v_rcp_f32_e32 v103, v103
	v_pk_mul_f32 v[104:105], v[104:105], v[108:109]
	v_pk_mul_f32 v[106:107], v[106:107], v[110:111]
	v_pk_mul_f32 v[96:97], v[96:97], v[100:101]
	v_pk_mul_f32 v[98:99], v[98:99], v[102:103]
	v_cvt_pk_bf16_f32 v212, v104, v105
	v_cvt_pk_bf16_f32 v213, v106, v107
	v_cvt_pk_bf16_f32 v214, v96, v97
	v_cvt_pk_bf16_f32 v215, v98, v99
	v_lshl_add_u64 v[176:177], s[68:69], 0, v[132:133]
	global_store_dwordx4 v[176:177], v[212:215], off sc1
	v_pk_mul_f32 v[92:93], v[92:93], v[164:165] op_sel:[0,1] op_sel_hi:[1,1]
; __device__ __forceinline__ unsigned cvt_pk_bf16(float lo, float hi) { unsigned r; asm volatile("v_cvt_pk_bf16_f32 %0, %1, %2" : "=v"(r) : "v"(lo), "v"(hi)); return r; }
;     __device__ __forceinline__ void operator()(f32x4 (&acc)[2][2][4][2], const Unit& u, int wr, int wc, int fr, int fq) const {
;     ...
;         for (int ai = 0; ai < 2; ++ai)
; #pragma unroll
;             for (int m = 0; m < 4; ++m) { const float ms = sq[ai][m] * (1.0f / 1024.0f) + 1e-6f, nrl = -__builtin_amdgcn_rsqf(ms) * LOG2E;
;                 float o[8];
; #pragma unroll
;                 for (int n = 0; n < 2; ++n)
; #pragma unroll
;                     for (int e = 0; e < 4; ++e) { const float a = acc[ai][0][m][n][e], bb = acc[ai][1][m][n][e];
;                         o[4 * n + e] = (a * bb) * __builtin_amdgcn_rcpf(__builtin_fmaf(__builtin_amdgcn_exp2f(a * nrl), ms, ms)); }
;                 u32x4 w; w.x = cvt_pk_bf16(o[0], o[1]); w.y = cvt_pk_bf16(o[2], o[3]); w.z = cvt_pk_bf16(o[4], o[5]); w.w = cvt_pk_bf16(o[6], o[7]);
;                 *(u32x4*)((char*)Ob + ai * HTB + lds_byte(wr * 64 + m * 16 + fr, (col0 & 63))) = w; }
	v_pk_mul_f32 v[94:95], v[94:95], v[164:165] op_sel:[0,1] op_sel_hi:[1,1]
	v_pk_mul_f32 v[84:85], v[84:85], v[164:165] op_sel:[0,1] op_sel_hi:[1,1]
	v_pk_mul_f32 v[86:87], v[86:87], v[164:165] op_sel:[0,1] op_sel_hi:[1,1]
	v_exp_f32_e32 v92, v92
	v_exp_f32_e32 v93, v93
	v_exp_f32_e32 v94, v94
	v_exp_f32_e32 v95, v95
	v_exp_f32_e32 v84, v84
	v_exp_f32_e32 v85, v85
	v_exp_f32_e32 v86, v86
	v_exp_f32_e32 v87, v87
	v_pk_fma_f32 v[92:93], v[92:93], v[164:165], v[164:165] op_sel_hi:[1,0,0]
	v_pk_fma_f32 v[94:95], v[94:95], v[164:165], v[164:165] op_sel_hi:[1,0,0]
	v_pk_fma_f32 v[84:85], v[84:85], v[164:165], v[164:165] op_sel_hi:[1,0,0]
	v_pk_fma_f32 v[86:87], v[86:87], v[164:165], v[164:165] op_sel_hi:[1,0,0]
	v_rcp_f32_e32 v92, v92
	v_rcp_f32_e32 v93, v93
	v_rcp_f32_e32 v94, v94
	v_rcp_f32_e32 v95, v95
	v_rcp_f32_e32 v84, v84
	v_rcp_f32_e32 v85, v85
	v_rcp_f32_e32 v86, v86
	v_rcp_f32_e32 v87, v87
	v_pk_mul_f32 v[88:89], v[88:89], v[92:93]
	v_pk_mul_f32 v[90:91], v[90:91], v[94:95]
	v_pk_mul_f32 v[80:81], v[80:81], v[84:85]
	v_pk_mul_f32 v[82:83], v[82:83], v[86:87]
	v_cvt_pk_bf16_f32 v208, v88, v89
	v_cvt_pk_bf16_f32 v209, v90, v91
	v_cvt_pk_bf16_f32 v210, v80, v81
	v_cvt_pk_bf16_f32 v211, v82, v83
	v_lshl_add_u64 v[176:177], s[68:69], 0, v[134:135]
	global_store_dwordx4 v[176:177], v[208:211], off sc1
	v_pk_mul_f32 v[76:77], v[76:77], v[166:167] op_sel:[0,1] op_sel_hi:[1,1]
	v_pk_mul_f32 v[78:79], v[78:79], v[166:167] op_sel:[0,1] op_sel_hi:[1,1]
	v_pk_mul_f32 v[68:69], v[68:69], v[166:167] op_sel:[0,1] op_sel_hi:[1,1]
	v_pk_mul_f32 v[70:71], v[70:71], v[166:167] op_sel:[0,1] op_sel_hi:[1,1]
	v_exp_f32_e32 v76, v76
	v_exp_f32_e32 v77, v77
	v_exp_f32_e32 v78, v78
	v_exp_f32_e32 v79, v79
	v_exp_f32_e32 v68, v68
	v_exp_f32_e32 v69, v69
	v_exp_f32_e32 v70, v70
	v_exp_f32_e32 v71, v71
	v_pk_fma_f32 v[76:77], v[76:77], v[166:167], v[166:167] op_sel_hi:[1,0,0]
	v_pk_fma_f32 v[78:79], v[78:79], v[166:167], v[166:167] op_sel_hi:[1,0,0]
	v_pk_fma_f32 v[68:69], v[68:69], v[166:167], v[166:167] op_sel_hi:[1,0,0]
	v_pk_fma_f32 v[70:71], v[70:71], v[166:167], v[166:167] op_sel_hi:[1,0,0]
	v_rcp_f32_e32 v76, v76
	v_rcp_f32_e32 v77, v77
	v_rcp_f32_e32 v78, v78
	v_rcp_f32_e32 v79, v79
	v_rcp_f32_e32 v68, v68
	v_rcp_f32_e32 v69, v69
	v_rcp_f32_e32 v70, v70
	v_rcp_f32_e32 v71, v71
	v_pk_mul_f32 v[72:73], v[72:73], v[76:77]
	v_pk_mul_f32 v[74:75], v[74:75], v[78:79]
	v_pk_mul_f32 v[64:65], v[64:65], v[68:69]
	v_pk_mul_f32 v[66:67], v[66:67], v[70:71]
	v_cvt_pk_bf16_f32 v212, v72, v73
	v_cvt_pk_bf16_f32 v213, v74, v75
	v_cvt_pk_bf16_f32 v214, v64, v65
	v_cvt_pk_bf16_f32 v215, v66, v67
	v_lshl_add_u64 v[176:177], s[68:69], 0, v[136:137]
	global_store_dwordx4 v[176:177], v[212:215], off sc1
	s_add_u32 s68, s68, 0x4000
	s_addc_u32 s69, s69, 0
	v_pk_mul_f32 v[60:61], v[60:61], v[168:169] op_sel:[0,1] op_sel_hi:[1,1]
	v_pk_mul_f32 v[62:63], v[62:63], v[168:169] op_sel:[0,1] op_sel_hi:[1,1]
	v_pk_mul_f32 v[52:53], v[52:53], v[168:169] op_sel:[0,1] op_sel_hi:[1,1]
	v_pk_mul_f32 v[54:55], v[54:55], v[168:169] op_sel:[0,1] op_sel_hi:[1,1]
	v_exp_f32_e32 v60, v60
	v_exp_f32_e32 v61, v61
	v_exp_f32_e32 v62, v62
	v_exp_f32_e32 v63, v63
	v_exp_f32_e32 v52, v52
	v_exp_f32_e32 v53, v53
	v_exp_f32_e32 v54, v54
	v_exp_f32_e32 v55, v55
	v_pk_fma_f32 v[60:61], v[60:61], v[168:169], v[168:169] op_sel_hi:[1,0,0]
	v_pk_fma_f32 v[62:63], v[62:63], v[168:169], v[168:169] op_sel_hi:[1,0,0]
	v_pk_fma_f32 v[52:53], v[52:53], v[168:169], v[168:169] op_sel_hi:[1,0,0]
	v_pk_fma_f32 v[54:55], v[54:55], v[168:169], v[168:169] op_sel_hi:[1,0,0]
	v_rcp_f32_e32 v60, v60
	v_rcp_f32_e32 v61, v61
	v_rcp_f32_e32 v62, v62
	v_rcp_f32_e32 v63, v63
	v_rcp_f32_e32 v52, v52
	v_rcp_f32_e32 v53, v53
	v_rcp_f32_e32 v54, v54
	v_rcp_f32_e32 v55, v55
	v_pk_mul_f32 v[56:57], v[56:57], v[60:61]
	v_pk_mul_f32 v[58:59], v[58:59], v[62:63]
	v_pk_mul_f32 v[48:49], v[48:49], v[52:53]
	v_pk_mul_f32 v[50:51], v[50:51], v[54:55]
	v_cvt_pk_bf16_f32 v208, v56, v57
	v_cvt_pk_bf16_f32 v209, v58, v59
	v_cvt_pk_bf16_f32 v210, v48, v49
	v_cvt_pk_bf16_f32 v211, v50, v51
	v_lshl_add_u64 v[176:177], s[68:69], 0, v[130:131]
	global_store_dwordx4 v[176:177], v[208:211], off sc1
	v_pk_mul_f32 v[44:45], v[44:45], v[170:171] op_sel:[0,1] op_sel_hi:[1,1]
; __device__ __forceinline__ unsigned cvt_pk_bf16(float lo, float hi) { unsigned r; asm volatile("v_cvt_pk_bf16_f32 %0, %1, %2" : "=v"(r) : "v"(lo), "v"(hi)); return r; }
; #define PG8_BAR __builtin_amdgcn_s_barrier()
;     __device__ __forceinline__ void operator()(f32x4 (&acc)[2][2][4][2], const Unit& u, int wr, int wc, int fr, int fq) const {
;     ...
;         for (int ai = 0; ai < 2; ++ai)
; #pragma unroll
;             for (int m = 0; m < 4; ++m) { const float ms = sq[ai][m] * (1.0f / 1024.0f) + 1e-6f, nrl = -__builtin_amdgcn_rsqf(ms) * LOG2E;
;                 float o[8];
; #pragma unroll
;                 for (int n = 0; n < 2; ++n)
; #pragma unroll
;                     for (int e = 0; e < 4; ++e) { const float a = acc[ai][0][m][n][e], bb = acc[ai][1][m][n][e];
;                         o[4 * n + e] = (a * bb) * __builtin_amdgcn_rcpf(__builtin_fmaf(__builtin_amdgcn_exp2f(a * nrl), ms, ms)); }
;                 u32x4 w; w.x = cvt_pk_bf16(o[0], o[1]); w.y = cvt_pk_bf16(o[2], o[3]); w.z = cvt_pk_bf16(o[4], o[5]); w.w = cvt_pk_bf16(o[6], o[7]);
;                 *(u32x4*)((char*)Ob + ai * HTB + lds_byte(wr * 64 + m * 16 + fr, (col0 & 63))) = w; }
; template <class Epi, class Sched, bool ALIGN_EPI = false, bool SP2 = false>
; __device__ __forceinline__ void gemm_phase(PG8_LAS unsigned char* lds, const Gemm g, const Sched& S, const Epi& E) {
;     ...
;         if (!has_next) break;
; #pragma unroll
;         for (int a = 0; a < 2; ++a)
; #pragma unroll
;             for (int b = 0; b < 2; ++b)
; #pragma unroll
;                 for (int m = 0; m < 4; ++m)
; #pragma unroll
;                     for (int n = 0; n < 2; ++n) acc[a][b][m][n] = (f32x4){0.f, 0.f, 0.f, 0.f};
;         cur = nxt; cA = nA; cB = nB; ++ui;
;         if constexpr (ALIGN_EPI) { if (wr == 1) PG8_BAR; }
	v_pk_mul_f32 v[46:47], v[46:47], v[170:171] op_sel:[0,1] op_sel_hi:[1,1]
	v_pk_mul_f32 v[36:37], v[36:37], v[170:171] op_sel:[0,1] op_sel_hi:[1,1]
	v_pk_mul_f32 v[38:39], v[38:39], v[170:171] op_sel:[0,1] op_sel_hi:[1,1]
	v_exp_f32_e32 v44, v44
	v_exp_f32_e32 v45, v45
	v_exp_f32_e32 v46, v46
	v_exp_f32_e32 v47, v47
	v_exp_f32_e32 v36, v36
	v_exp_f32_e32 v37, v37
	v_exp_f32_e32 v38, v38
	v_exp_f32_e32 v39, v39
	v_pk_fma_f32 v[44:45], v[44:45], v[170:171], v[170:171] op_sel_hi:[1,0,0]
	v_pk_fma_f32 v[46:47], v[46:47], v[170:171], v[170:171] op_sel_hi:[1,0,0]
	v_pk_fma_f32 v[36:37], v[36:37], v[170:171], v[170:171] op_sel_hi:[1,0,0]
	v_pk_fma_f32 v[38:39], v[38:39], v[170:171], v[170:171] op_sel_hi:[1,0,0]
	v_rcp_f32_e32 v44, v44
	v_rcp_f32_e32 v45, v45
	v_rcp_f32_e32 v46, v46
	v_rcp_f32_e32 v47, v47
	v_rcp_f32_e32 v36, v36
	v_rcp_f32_e32 v37, v37
	v_rcp_f32_e32 v38, v38
	v_rcp_f32_e32 v39, v39
	v_pk_mul_f32 v[40:41], v[40:41], v[44:45]
	v_pk_mul_f32 v[42:43], v[42:43], v[46:47]
	v_pk_mul_f32 v[32:33], v[32:33], v[36:37]
	v_pk_mul_f32 v[34:35], v[34:35], v[38:39]
	v_cvt_pk_bf16_f32 v212, v40, v41
	v_cvt_pk_bf16_f32 v213, v42, v43
	v_cvt_pk_bf16_f32 v214, v32, v33
	v_cvt_pk_bf16_f32 v215, v34, v35
	v_lshl_add_u64 v[176:177], s[68:69], 0, v[132:133]
	global_store_dwordx4 v[176:177], v[212:215], off sc1
	v_pk_mul_f32 v[28:29], v[28:29], v[172:173] op_sel:[0,1] op_sel_hi:[1,1]
	v_pk_mul_f32 v[30:31], v[30:31], v[172:173] op_sel:[0,1] op_sel_hi:[1,1]
	v_pk_mul_f32 v[20:21], v[20:21], v[172:173] op_sel:[0,1] op_sel_hi:[1,1]
	v_pk_mul_f32 v[22:23], v[22:23], v[172:173] op_sel:[0,1] op_sel_hi:[1,1]
	v_exp_f32_e32 v28, v28
	v_exp_f32_e32 v29, v29
	v_exp_f32_e32 v30, v30
	v_exp_f32_e32 v31, v31
	v_exp_f32_e32 v20, v20
	v_exp_f32_e32 v21, v21
	v_exp_f32_e32 v22, v22
	v_exp_f32_e32 v23, v23
	v_pk_fma_f32 v[28:29], v[28:29], v[172:173], v[172:173] op_sel_hi:[1,0,0]
	v_pk_fma_f32 v[30:31], v[30:31], v[172:173], v[172:173] op_sel_hi:[1,0,0]
	v_pk_fma_f32 v[20:21], v[20:21], v[172:173], v[172:173] op_sel_hi:[1,0,0]
	v_pk_fma_f32 v[22:23], v[22:23], v[172:173], v[172:173] op_sel_hi:[1,0,0]
	v_rcp_f32_e32 v28, v28
	v_rcp_f32_e32 v29, v29
	v_rcp_f32_e32 v30, v30
	v_rcp_f32_e32 v31, v31
	v_rcp_f32_e32 v20, v20
	v_rcp_f32_e32 v21, v21
	v_rcp_f32_e32 v22, v22
	v_rcp_f32_e32 v23, v23
	v_pk_mul_f32 v[24:25], v[24:25], v[28:29]
	v_pk_mul_f32 v[26:27], v[26:27], v[30:31]
	v_pk_mul_f32 v[16:17], v[16:17], v[20:21]
	v_pk_mul_f32 v[18:19], v[18:19], v[22:23]
	v_cvt_pk_bf16_f32 v208, v24, v25
	v_cvt_pk_bf16_f32 v209, v26, v27
	v_cvt_pk_bf16_f32 v210, v16, v17
	v_cvt_pk_bf16_f32 v211, v18, v19
	v_lshl_add_u64 v[176:177], s[68:69], 0, v[134:135]
	global_store_dwordx4 v[176:177], v[208:211], off sc1
	v_pk_mul_f32 v[12:13], v[12:13], v[174:175] op_sel:[0,1] op_sel_hi:[1,1]
	v_pk_mul_f32 v[14:15], v[14:15], v[174:175] op_sel:[0,1] op_sel_hi:[1,1]
	v_pk_mul_f32 v[4:5], v[4:5], v[174:175] op_sel:[0,1] op_sel_hi:[1,1]
	v_pk_mul_f32 v[6:7], v[6:7], v[174:175] op_sel:[0,1] op_sel_hi:[1,1]
	v_exp_f32_e32 v12, v12
	v_exp_f32_e32 v13, v13
	v_exp_f32_e32 v14, v14
	v_exp_f32_e32 v15, v15
	v_exp_f32_e32 v4, v4
	v_exp_f32_e32 v5, v5
	v_exp_f32_e32 v6, v6
	v_exp_f32_e32 v7, v7
	v_pk_fma_f32 v[12:13], v[12:13], v[174:175], v[174:175] op_sel_hi:[1,0,0]
	v_pk_fma_f32 v[14:15], v[14:15], v[174:175], v[174:175] op_sel_hi:[1,0,0]
	v_pk_fma_f32 v[4:5], v[4:5], v[174:175], v[174:175] op_sel_hi:[1,0,0]
	v_pk_fma_f32 v[6:7], v[6:7], v[174:175], v[174:175] op_sel_hi:[1,0,0]
	v_rcp_f32_e32 v12, v12
	v_rcp_f32_e32 v13, v13
	v_rcp_f32_e32 v14, v14
	v_rcp_f32_e32 v15, v15
	v_rcp_f32_e32 v4, v4
	v_rcp_f32_e32 v5, v5
	v_rcp_f32_e32 v6, v6
	v_rcp_f32_e32 v7, v7
	v_pk_mul_f32 v[8:9], v[8:9], v[12:13]
	v_pk_mul_f32 v[10:11], v[10:11], v[14:15]
	v_pk_mul_f32 v[0:1], v[0:1], v[4:5]
	v_pk_mul_f32 v[2:3], v[2:3], v[6:7]
	v_cvt_pk_bf16_f32 v212, v8, v9
	v_cvt_pk_bf16_f32 v213, v10, v11
	v_cvt_pk_bf16_f32 v214, v0, v1
	v_cvt_pk_bf16_f32 v215, v2, v3
	v_lshl_add_u64 v[176:177], s[68:69], 0, v[136:137]
	global_store_dwordx4 v[176:177], v[212:215], off sc1
	s_andn2_b64 vcc, exec, s[2:3]
	s_mov_b64 s[2:3], -1
	s_cbranch_vccnz .LBB0_137
	s_andn2_b64 vcc, exec, s[52:53]
	s_cbranch_vccnz .LBB0_136
	s_barrier
	s_branch .LBB0_136

; #define PG8_STAGE(bufoff, gbase, voff) do { _Pragma("unroll") for (int _i = 0; _i < 2; ++_i) \
;         __builtin_amdgcn_global_load_lds((const unsigned*)((const char*)(gbase) + (voff)[_i]), (PG8_LAS unsigned*)(lds + (bufoff) + ldsw + _i * 8192), 16, 0, 0); } while (0)
; #define PG8_LDA(dst, b, h) do { _Pragma("unroll") for (int m = 0; m < 4; ++m) _Pragma("unroll") for (int k = 0; k < 2; ++k) dst[m][k] = *(const PG8_LAS bf16x8*)(lds + PG8_SA(b, h) + aoff + m * 2048 + k * 1024); } while (0)
; #define PG8_LDB(dst, b, h) do { _Pragma("unroll") for (int n = 0; n < 2; ++n) _Pragma("unroll") for (int k = 0; k < 2; ++k) dst[n][k] = *(const PG8_LAS bf16x8*)(lds + PG8_SB(b, h) + boff + n * 2048 + k * 1024); } while (0)
; #define PG8_WAIT_V(n) asm volatile("s_waitcnt vmcnt(" #n ")" ::: "memory")
; #define PG8_WAIT_L(n) asm volatile("s_waitcnt lgkmcnt(" #n ")" ::: "memory")
; #define PG8_BAR __builtin_amdgcn_s_barrier()
; #define PG8_SCHED __builtin_amdgcn_sched_barrier(0)
;     __device__ __forceinline__ void operator()(f32x4 (&acc)[2][2][4][2], const Unit& u, int wr, int wc, int fr, int fq) const {
;     ...
;         for (int ai = 0; ai < 2; ++ai)
; #pragma unroll
;             for (int m = 0; m < 4; ++m) sq[ai][m] = ssq[row0 + ai * HALF + m * 16];
; template <class Epi, class Sched, bool ALIGN_EPI = false, bool SP2 = false>
; __device__ __forceinline__ void gemm_phase(PG8_LAS unsigned char* lds, const Gemm g, const Sched& S, const Epi& E) {
;     ...
;         const bool has_next = S.next(ui + 1, nxt);
;         const char* nA = has_next ? (const char*)g.A + (size_t)nxt.pm * tstepA : cA; const char* nB = has_next ? (const char*)g.Bt + (size_t)nxt.pn * tstepB : cB;
;         for (int t = 0; t < nt; t += 2) {
;             const bool last = (t == nt - 2);
;             const char* a1 = cA + (size_t)(t + 1) * kstepA;
;             const char* a2 = last ? nA : cA + (size_t)(t + 2) * kstepA; const char* b2 = last ? nB : cB + (size_t)(t + 2) * kstep;
;             const char* a3 = a2 + kstepA; const char* b3 = b2 + kstep;
;             if (last && has_next) S.a_ready(nxt);
;             if constexpr (SP2) {
;             PG8_LDB(B0, 0, 0); PG8_LDB(B1, 0, 1); PG8_SCHED; PG8_LDA(At, 0, 0); PG8_STAGE(PG8_SA(1, 1), a1 + hstepA, voffA);
;             PG8_WAIT_V(8); PG8_WAIT_L(0); PG8_BAR; PG8_MMA(0, 0, At, B0); PG8_MMA(0, 1, At, B1); PG8_BAR; PG8_SCHED;
.LBB0_835:
	v_lshl_add_u32 v148, s60, 8, v140
	v_ashrrev_i32_e32 v149, 31, v148
	v_lshl_add_u64 v[148:149], v[148:149], 2, s[0:1]
	global_load_dword v247, v[148:149], off
	global_load_dword v248, v[148:149], off offset:64
	global_load_dword v249, v[148:149], off offset:128
	global_load_dword v250, v[148:149], off offset:192
	global_load_dword v251, v[148:149], off offset:512
	global_load_dword v252, v[148:149], off offset:576
	global_load_dword v253, v[148:149], off offset:640
	global_load_dword v254, v[148:149], off offset:704
	s_add_i32 s70, s70, 1
	s_mul_i32 s2, s70, s72
	s_mul_hi_u32 s3, s70, s73
	s_add_i32 s3, s3, s2
	s_mul_i32 s2, s70, s73
	s_add_u32 s56, s2, s16
	s_addc_u32 s57, s3, s15
	v_cmp_gt_i64_e32 vcc, s[56:57], v[138:139]
	v_cmp_lt_i64_e64 s[2:3], s[56:57], v[136:137]
	s_cbranch_vccnz .LBB0_837
	s_ashr_i32 s52, s56, 31
	s_lshr_b32 s52, s52, 29
	s_add_i32 s52, s56, s52
	s_ashr_i32 s53, s52, 3
	s_and_b32 s52, s52, -8
	s_sub_i32 s52, s56, s52
	s_cmp_lt_i32 s52, 0
	s_cselect_b32 s54, s17, 0x160
	s_mul_i32 s52, s52, s54
	s_add_i32 s52, s52, s53
	s_mul_hi_i32 s53, s52, 0x2e8ba2e9
	s_lshr_b32 s54, s53, 31
	s_ashr_i32 s53, s53, 4
	s_add_i32 s53, s53, s54
	s_lshl_b32 s54, s53, 2
	s_mulk_i32 s53, 0x58
	s_sub_i32 s53, s52, s53
	s_abs_i32 s52, s53
	s_ashr_i32 s52, s53, 2
	s_and_b32 s53, s53, 3
	s_add_i32 s54, s54, s53
.LBB0_837:
	s_ashr_i32 s55, s54, 31
	s_lshl_b64 s[56:57], s[54:55], 19
	s_add_u32 s56, s12, s56
	s_addc_u32 s57, s13, s57
	s_and_b64 s[58:59], s[2:3], exec
	s_cselect_b32 s55, s57, s63
	s_cselect_b32 s80, s56, s62
	s_ashr_i32 s53, s52, 31
	s_lshl_b64 s[58:59], s[52:53], 19
	s_add_u32 s58, s33, s58
	s_addc_u32 s59, s83, s59
	s_and_b64 s[78:79], s[2:3], exec
	s_cselect_b32 s53, s59, s65
	s_cselect_b32 s81, s58, s64
	s_add_u32 s62, s62, 0x10000
	s_addc_u32 s63, s63, 0
	s_add_u32 s64, s64, 0x10000
	s_addc_u32 s65, s65, 0
	s_mov_b32 s82, -2
	ds_read_b128 v[148:151], v141
	ds_read_b128 v[152:155], v141 offset:1024
	ds_read_b128 v[156:159], v141 offset:2048
	ds_read_b128 v[160:163], v141 offset:3072
	ds_read_b128 v[164:167], v142
	ds_read_b128 v[168:171], v142 offset:1024
	ds_read_b128 v[172:175], v142 offset:2048
	ds_read_b128 v[176:179], v142 offset:3072
	s_cmp_eq_u32 s82, 12
	s_cselect_b32 s79, s55, s63
	s_cselect_b32 s78, s80, s62
	s_cselect_b32 s85, s53, s65
	s_cselect_b32 s84, s81, s64
	v_lshl_add_u64 v[216:217], s[62:63], 0, v[190:191]
	v_lshl_add_u64 v[220:221], v[216:217], 0, s[46:47]
	s_add_i32 m0, s18, 0xc000
	ds_read_b128 v[180:183], v143
	ds_read_b128 v[184:187], v143 offset:1024
	ds_read_b128 v[192:195], v143 offset:2048
	ds_read_b128 v[196:199], v143 offset:3072
	ds_read_b128 v[200:203], v143 offset:4096
	ds_read_b128 v[204:207], v143 offset:5120
	ds_read_b128 v[208:211], v143 offset:6144
	ds_read_b128 v[212:215], v143 offset:7168
	global_load_lds_dwordx4 v[220:221], off
	v_lshl_add_u64 v[216:217], v[216:217], 0, s[48:49]
	s_add_i32 m0, s18, 0xe000
	s_nop 0
	global_load_lds_dwordx4 v[216:217], off
	s_waitcnt vmcnt(24)
	s_waitcnt lgkmcnt(0)
	s_barrier
	s_waitcnt lgkmcnt(0)
	v_mfma_f32_16x16x32_bf16 v[116:119], v[148:151], v[180:183], 0
	v_mfma_f32_16x16x32_bf16 v[112:115], v[156:159], v[180:183], 0
	v_mfma_f32_16x16x32_bf16 v[108:111], v[148:151], v[192:195], 0
	v_mfma_f32_16x16x32_bf16 v[100:103], v[156:159], v[192:195], 0
	v_mfma_f32_16x16x32_bf16 v[92:95], v[148:151], v[200:203], 0
	v_mfma_f32_16x16x32_bf16 v[84:87], v[156:159], v[200:203], 0
	v_mfma_f32_16x16x32_bf16 v[76:79], v[148:151], v[208:211], 0
	v_mfma_f32_16x16x32_bf16 v[68:71], v[156:159], v[208:211], 0
	v_mfma_f32_16x16x32_bf16 v[116:119], v[152:155], v[184:187], v[116:119]
	v_mfma_f32_16x16x32_bf16 v[112:115], v[160:163], v[184:187], v[112:115]
	v_mfma_f32_16x16x32_bf16 v[108:111], v[152:155], v[196:199], v[108:111]
	v_mfma_f32_16x16x32_bf16 v[100:103], v[160:163], v[196:199], v[100:103]
	v_mfma_f32_16x16x32_bf16 v[92:95], v[152:155], v[204:207], v[92:95]
	v_mfma_f32_16x16x32_bf16 v[84:87], v[160:163], v[204:207], v[84:87]
	v_mfma_f32_16x16x32_bf16 v[76:79], v[152:155], v[212:215], v[76:79]
	v_mfma_f32_16x16x32_bf16 v[68:71], v[160:163], v[212:215], v[68:71]
	v_mfma_f32_16x16x32_bf16 v[124:127], v[164:167], v[180:183], 0
	v_mfma_f32_16x16x32_bf16 v[120:123], v[172:175], v[180:183], 0
	v_mfma_f32_16x16x32_bf16 v[104:107], v[164:167], v[192:195], 0
	v_mfma_f32_16x16x32_bf16 v[96:99], v[172:175], v[192:195], 0
	v_mfma_f32_16x16x32_bf16 v[88:91], v[164:167], v[200:203], 0
	v_mfma_f32_16x16x32_bf16 v[80:83], v[172:175], v[200:203], 0
	v_mfma_f32_16x16x32_bf16 v[72:75], v[164:167], v[208:211], 0
	v_mfma_f32_16x16x32_bf16 v[64:67], v[172:175], v[208:211], 0
	v_mfma_f32_16x16x32_bf16 v[124:127], v[168:171], v[184:187], v[124:127]
	v_mfma_f32_16x16x32_bf16 v[120:123], v[176:179], v[184:187], v[120:123]
	v_mfma_f32_16x16x32_bf16 v[104:107], v[168:171], v[196:199], v[104:107]
	v_mfma_f32_16x16x32_bf16 v[96:99], v[176:179], v[196:199], v[96:99]
	v_mfma_f32_16x16x32_bf16 v[88:91], v[168:171], v[204:207], v[88:91]
	v_mfma_f32_16x16x32_bf16 v[80:83], v[176:179], v[204:207], v[80:83]
	v_mfma_f32_16x16x32_bf16 v[72:75], v[168:171], v[212:215], v[72:75]
	v_mfma_f32_16x16x32_bf16 v[64:67], v[176:179], v[212:215], v[64:67]
	s_barrier
; #define PG8_STAGE(bufoff, gbase, voff) do { _Pragma("unroll") for (int _i = 0; _i < 2; ++_i) \
;         __builtin_amdgcn_global_load_lds((const unsigned*)((const char*)(gbase) + (voff)[_i]), (PG8_LAS unsigned*)(lds + (bufoff) + ldsw + _i * 8192), 16, 0, 0); } while (0)
; #define PG8_LDA(dst, b, h) do { _Pragma("unroll") for (int m = 0; m < 4; ++m) _Pragma("unroll") for (int k = 0; k < 2; ++k) dst[m][k] = *(const PG8_LAS bf16x8*)(lds + PG8_SA(b, h) + aoff + m * 2048 + k * 1024); } while (0)
; #define PG8_LDB(dst, b, h) do { _Pragma("unroll") for (int n = 0; n < 2; ++n) _Pragma("unroll") for (int k = 0; k < 2; ++k) dst[n][k] = *(const PG8_LAS bf16x8*)(lds + PG8_SB(b, h) + boff + n * 2048 + k * 1024); } while (0)
; #define PG8_MMA(ai, bj, At, Bt) do { __builtin_amdgcn_s_setprio(1); _Pragma("unroll") for (int m = 0; m < 4; ++m) _Pragma("unroll") for (int n = 0; n < 2; ++n) _Pragma("unroll") for (int k = 0; k < 2; ++k) \
;         acc[ai][bj][m][n] = __builtin_amdgcn_mfma_f32_16x16x32_bf16(Bt[n][k], At[m][k], acc[ai][bj][m][n], 0, 0, 0); __builtin_amdgcn_s_setprio(0); } while (0)
; #define PG8_WAIT_V(n) asm volatile("s_waitcnt vmcnt(" #n ")" ::: "memory")
; #define PG8_WAIT_L(n) asm volatile("s_waitcnt lgkmcnt(" #n ")" ::: "memory")
; #define PG8_BAR __builtin_amdgcn_s_barrier()
; #define PG8_SCHED __builtin_amdgcn_sched_barrier(0)
; template <class Epi, class Sched, bool ALIGN_EPI = false, bool SP2 = false>
; __device__ __forceinline__ void gemm_phase(PG8_LAS unsigned char* lds, const Gemm g, const Sched& S, const Epi& E) {
;     ...
;             PG8_LDA(At, 0, 1); PG8_STAGE(PG8_SB(0, 0), b2, voffB); PG8_STAGE(PG8_SB(0, 1), b2 + hstepB, voffB); PG8_STAGE(PG8_SA(0, 0), a2, voffA);
;             PG8_WAIT_V(8); PG8_WAIT_L(0); PG8_BAR; PG8_MMA(1, 0, At, B0); PG8_MMA(1, 1, At, B1); PG8_BAR; PG8_SCHED;
;             PG8_LDB(B0, 1, 0); PG8_LDB(B1, 1, 1); PG8_SCHED; PG8_LDA(At, 1, 0); PG8_STAGE(PG8_SA(0, 1), a2 + hstepA, voffA);
	v_lshl_add_u64 v[216:217], s[84:85], 0, v[190:191]
	s_add_i32 s84, s74, s14
	s_mov_b32 m0, s84
	ds_read_b128 v[180:183], v143 offset:16384
	ds_read_b128 v[184:187], v143 offset:17408
	ds_read_b128 v[192:195], v143 offset:18432
	ds_read_b128 v[196:199], v143 offset:19456
	ds_read_b128 v[200:203], v143 offset:20480
	ds_read_b128 v[204:207], v143 offset:21504
	ds_read_b128 v[208:211], v143 offset:22528
	ds_read_b128 v[212:215], v143 offset:23552
	global_load_lds_dwordx4 v[216:217], off
	v_lshl_add_u64 v[220:221], v[216:217], 0, s[6:7]
	s_add_i32 m0, s84, 0x2000
	s_add_i32 s84, s75, s14
	global_load_lds_dwordx4 v[220:221], off
	v_lshl_add_u64 v[220:221], v[216:217], 0, s[8:9]
	s_mov_b32 m0, s84
	s_nop 0
	global_load_lds_dwordx4 v[220:221], off
	v_lshl_add_u64 v[220:221], v[216:217], 0, s[10:11]
	s_add_i32 m0, s84, 0x2000
	s_nop 0
	global_load_lds_dwordx4 v[220:221], off
	v_lshl_add_u64 v[220:221], s[78:79], 0, v[190:191]
	s_mov_b32 m0, s18
	v_lshl_add_u64 v[222:223], v[220:221], 0, s[6:7]
	global_load_lds_dwordx4 v[220:221], off
	s_mov_b32 m0, s19
	s_nop 0
	global_load_lds_dwordx4 v[222:223], off
	s_waitcnt vmcnt(24)
	s_waitcnt lgkmcnt(0)
	s_barrier
	s_waitcnt lgkmcnt(0)
	v_mfma_f32_16x16x32_bf16 v[60:63], v[148:151], v[180:183], 0
	v_mfma_f32_16x16x32_bf16 v[52:55], v[156:159], v[180:183], 0
	v_mfma_f32_16x16x32_bf16 v[44:47], v[148:151], v[192:195], 0
	v_mfma_f32_16x16x32_bf16 v[36:39], v[156:159], v[192:195], 0
	v_mfma_f32_16x16x32_bf16 v[28:31], v[148:151], v[200:203], 0
	v_mfma_f32_16x16x32_bf16 v[20:23], v[156:159], v[200:203], 0
	v_mfma_f32_16x16x32_bf16 v[12:15], v[148:151], v[208:211], 0
	v_mfma_f32_16x16x32_bf16 v[4:7], v[156:159], v[208:211], 0
	v_mfma_f32_16x16x32_bf16 v[60:63], v[152:155], v[184:187], v[60:63]
	v_mfma_f32_16x16x32_bf16 v[52:55], v[160:163], v[184:187], v[52:55]
	v_mfma_f32_16x16x32_bf16 v[44:47], v[152:155], v[196:199], v[44:47]
	v_mfma_f32_16x16x32_bf16 v[36:39], v[160:163], v[196:199], v[36:39]
	v_mfma_f32_16x16x32_bf16 v[28:31], v[152:155], v[204:207], v[28:31]
	v_mfma_f32_16x16x32_bf16 v[20:23], v[160:163], v[204:207], v[20:23]
	v_mfma_f32_16x16x32_bf16 v[12:15], v[152:155], v[212:215], v[12:15]
	v_mfma_f32_16x16x32_bf16 v[4:7], v[160:163], v[212:215], v[4:7]
	v_mfma_f32_16x16x32_bf16 v[56:59], v[164:167], v[180:183], 0
	v_mfma_f32_16x16x32_bf16 v[48:51], v[172:175], v[180:183], 0
	v_mfma_f32_16x16x32_bf16 v[40:43], v[164:167], v[192:195], 0
	v_mfma_f32_16x16x32_bf16 v[32:35], v[172:175], v[192:195], 0
	v_mfma_f32_16x16x32_bf16 v[24:27], v[164:167], v[200:203], 0
	v_mfma_f32_16x16x32_bf16 v[16:19], v[172:175], v[200:203], 0
	v_mfma_f32_16x16x32_bf16 v[8:11], v[164:167], v[208:211], 0
	v_mfma_f32_16x16x32_bf16 v[0:3], v[172:175], v[208:211], 0
	v_mfma_f32_16x16x32_bf16 v[56:59], v[168:171], v[184:187], v[56:59]
	v_mfma_f32_16x16x32_bf16 v[48:51], v[176:179], v[184:187], v[48:51]
	v_mfma_f32_16x16x32_bf16 v[40:43], v[168:171], v[196:199], v[40:43]
	v_mfma_f32_16x16x32_bf16 v[32:35], v[176:179], v[196:199], v[32:35]
	v_mfma_f32_16x16x32_bf16 v[24:27], v[168:171], v[204:207], v[24:27]
	v_mfma_f32_16x16x32_bf16 v[16:19], v[176:179], v[204:207], v[16:19]
	v_mfma_f32_16x16x32_bf16 v[8:11], v[168:171], v[212:215], v[8:11]
	v_mfma_f32_16x16x32_bf16 v[0:3], v[176:179], v[212:215], v[0:3]
	s_barrier
	ds_read_b128 v[148:151], v144
	ds_read_b128 v[152:155], v144 offset:1024
	ds_read_b128 v[156:159], v144 offset:2048
	ds_read_b128 v[160:163], v144 offset:3072
	ds_read_b128 v[164:167], v145
	ds_read_b128 v[168:171], v145 offset:1024
	ds_read_b128 v[172:175], v145 offset:2048
	ds_read_b128 v[176:179], v145 offset:3072
	s_mov_b32 m0, s66
	v_lshl_add_u64 v[222:223], v[220:221], 0, s[8:9]
	ds_read_b128 v[180:183], v143 offset:32768
	ds_read_b128 v[184:187], v143 offset:33792
	ds_read_b128 v[192:195], v143 offset:34816
	ds_read_b128 v[196:199], v143 offset:35840
	ds_read_b128 v[200:203], v143 offset:36864
	ds_read_b128 v[204:207], v143 offset:37888
	ds_read_b128 v[208:211], v143 offset:38912
	ds_read_b128 v[212:215], v143 offset:39936
	global_load_lds_dwordx4 v[222:223], off
	v_lshl_add_u64 v[222:223], v[220:221], 0, s[10:11]
	s_mov_b32 m0, s67
	s_nop 0
	global_load_lds_dwordx4 v[222:223], off
	s_waitcnt vmcnt(8)
	s_waitcnt lgkmcnt(0)
	s_barrier
; #define PG8_STAGE(bufoff, gbase, voff) do { _Pragma("unroll") for (int _i = 0; _i < 2; ++_i) \
;         __builtin_amdgcn_global_load_lds((const unsigned*)((const char*)(gbase) + (voff)[_i]), (PG8_LAS unsigned*)(lds + (bufoff) + ldsw + _i * 8192), 16, 0, 0); } while (0)
; #define PG8_LDA(dst, b, h) do { _Pragma("unroll") for (int m = 0; m < 4; ++m) _Pragma("unroll") for (int k = 0; k < 2; ++k) dst[m][k] = *(const PG8_LAS bf16x8*)(lds + PG8_SA(b, h) + aoff + m * 2048 + k * 1024); } while (0)
; #define PG8_MMA(ai, bj, At, Bt) do { __builtin_amdgcn_s_setprio(1); _Pragma("unroll") for (int m = 0; m < 4; ++m) _Pragma("unroll") for (int n = 0; n < 2; ++n) _Pragma("unroll") for (int k = 0; k < 2; ++k) \
;         acc[ai][bj][m][n] = __builtin_amdgcn_mfma_f32_16x16x32_bf16(Bt[n][k], At[m][k], acc[ai][bj][m][n], 0, 0, 0); __builtin_amdgcn_s_setprio(0); } while (0)
; #define PG8_WAIT_V(n) asm volatile("s_waitcnt vmcnt(" #n ")" ::: "memory")
; #define PG8_WAIT_L(n) asm volatile("s_waitcnt lgkmcnt(" #n ")" ::: "memory")
; #define PG8_BAR __builtin_amdgcn_s_barrier()
; #define PG8_SCHED __builtin_amdgcn_sched_barrier(0)
; template <class Epi, class Sched, bool ALIGN_EPI = false, bool SP2 = false>
; __device__ __forceinline__ void gemm_phase(PG8_LAS unsigned char* lds, const Gemm g, const Sched& S, const Epi& E) {
;     ...
;             PG8_WAIT_V(8); PG8_WAIT_L(0); PG8_BAR; PG8_MMA(0, 0, At, B0); PG8_MMA(0, 1, At, B1); PG8_BAR; PG8_SCHED;
;             PG8_LDA(At, 1, 1); PG8_STAGE(PG8_SB(1, 0), b3, voffB); PG8_STAGE(PG8_SB(1, 1), b3 + hstepB, voffB); PG8_STAGE(PG8_SA(1, 0), a3, voffA);
;             PG8_WAIT_V(8); PG8_WAIT_L(0); PG8_BAR; PG8_MMA(1, 0, At, B0); PG8_MMA(1, 1, At, B1); PG8_BAR; PG8_SCHED;
	s_waitcnt lgkmcnt(0)
	v_mfma_f32_16x16x32_bf16 v[116:119], v[148:151], v[180:183], v[116:119]
	v_mfma_f32_16x16x32_bf16 v[112:115], v[156:159], v[180:183], v[112:115]
	v_mfma_f32_16x16x32_bf16 v[108:111], v[148:151], v[192:195], v[108:111]
	v_mfma_f32_16x16x32_bf16 v[100:103], v[156:159], v[192:195], v[100:103]
	v_mfma_f32_16x16x32_bf16 v[92:95], v[148:151], v[200:203], v[92:95]
	v_mfma_f32_16x16x32_bf16 v[84:87], v[156:159], v[200:203], v[84:87]
	v_mfma_f32_16x16x32_bf16 v[76:79], v[148:151], v[208:211], v[76:79]
	v_mfma_f32_16x16x32_bf16 v[68:71], v[156:159], v[208:211], v[68:71]
	v_mfma_f32_16x16x32_bf16 v[116:119], v[152:155], v[184:187], v[116:119]
	v_mfma_f32_16x16x32_bf16 v[112:115], v[160:163], v[184:187], v[112:115]
	v_mfma_f32_16x16x32_bf16 v[108:111], v[152:155], v[196:199], v[108:111]
	v_mfma_f32_16x16x32_bf16 v[100:103], v[160:163], v[196:199], v[100:103]
	v_mfma_f32_16x16x32_bf16 v[92:95], v[152:155], v[204:207], v[92:95]
	v_mfma_f32_16x16x32_bf16 v[84:87], v[160:163], v[204:207], v[84:87]
	v_mfma_f32_16x16x32_bf16 v[76:79], v[152:155], v[212:215], v[76:79]
	v_mfma_f32_16x16x32_bf16 v[68:71], v[160:163], v[212:215], v[68:71]
	v_mfma_f32_16x16x32_bf16 v[124:127], v[164:167], v[180:183], v[124:127]
	v_mfma_f32_16x16x32_bf16 v[120:123], v[172:175], v[180:183], v[120:123]
	v_mfma_f32_16x16x32_bf16 v[104:107], v[164:167], v[192:195], v[104:107]
	v_mfma_f32_16x16x32_bf16 v[96:99], v[172:175], v[192:195], v[96:99]
	v_mfma_f32_16x16x32_bf16 v[88:91], v[164:167], v[200:203], v[88:91]
	v_mfma_f32_16x16x32_bf16 v[80:83], v[172:175], v[200:203], v[80:83]
	v_mfma_f32_16x16x32_bf16 v[72:75], v[164:167], v[208:211], v[72:75]
	v_mfma_f32_16x16x32_bf16 v[64:67], v[172:175], v[208:211], v[64:67]
	v_mfma_f32_16x16x32_bf16 v[124:127], v[168:171], v[184:187], v[124:127]
	v_mfma_f32_16x16x32_bf16 v[120:123], v[176:179], v[184:187], v[120:123]
	v_mfma_f32_16x16x32_bf16 v[104:107], v[168:171], v[196:199], v[104:107]
	v_mfma_f32_16x16x32_bf16 v[96:99], v[176:179], v[196:199], v[96:99]
	v_mfma_f32_16x16x32_bf16 v[88:91], v[168:171], v[204:207], v[88:91]
	v_mfma_f32_16x16x32_bf16 v[80:83], v[176:179], v[204:207], v[80:83]
	v_mfma_f32_16x16x32_bf16 v[72:75], v[168:171], v[212:215], v[72:75]
	v_mfma_f32_16x16x32_bf16 v[64:67], v[176:179], v[212:215], v[64:67]
	s_barrier
	s_add_i32 s78, s76, s14
	v_lshl_add_u64 v[222:223], v[216:217], 0, s[34:35]
	s_mov_b32 m0, s78
	ds_read_b128 v[180:183], v143 offset:49152
	ds_read_b128 v[184:187], v143 offset:50176
	ds_read_b128 v[192:195], v143 offset:51200
	ds_read_b128 v[196:199], v143 offset:52224
	ds_read_b128 v[200:203], v143 offset:53248
	ds_read_b128 v[204:207], v143 offset:54272
	ds_read_b128 v[208:211], v143 offset:55296
	ds_read_b128 v[212:215], v143 offset:56320
	global_load_lds_dwordx4 v[222:223], off
	v_lshl_add_u64 v[222:223], v[216:217], 0, s[36:37]
	s_add_i32 m0, s78, 0x2000
	s_add_i32 s78, s77, s14
	global_load_lds_dwordx4 v[222:223], off
	v_lshl_add_u64 v[222:223], v[216:217], 0, s[38:39]
	s_mov_b32 m0, s78
	v_lshl_add_u64 v[216:217], v[216:217], 0, s[40:41]
	global_load_lds_dwordx4 v[222:223], off
	s_add_i32 m0, s78, 0x2000
	s_nop 0
	global_load_lds_dwordx4 v[216:217], off
	v_lshl_add_u64 v[216:217], v[220:221], 0, s[34:35]
	s_mov_b32 m0, s68
	s_nop 0
	global_load_lds_dwordx4 v[216:217], off
	v_lshl_add_u64 v[216:217], v[220:221], 0, s[36:37]
	s_mov_b32 m0, s69
	s_nop 0
	global_load_lds_dwordx4 v[216:217], off
	s_waitcnt vmcnt(8)
	s_waitcnt lgkmcnt(0)
	s_barrier
	s_waitcnt lgkmcnt(0)
	v_mfma_f32_16x16x32_bf16 v[60:63], v[148:151], v[180:183], v[60:63]
	v_mfma_f32_16x16x32_bf16 v[52:55], v[156:159], v[180:183], v[52:55]
	v_mfma_f32_16x16x32_bf16 v[44:47], v[148:151], v[192:195], v[44:47]
	v_mfma_f32_16x16x32_bf16 v[36:39], v[156:159], v[192:195], v[36:39]
	v_mfma_f32_16x16x32_bf16 v[28:31], v[148:151], v[200:203], v[28:31]
	v_mfma_f32_16x16x32_bf16 v[20:23], v[156:159], v[200:203], v[20:23]
	v_mfma_f32_16x16x32_bf16 v[12:15], v[148:151], v[208:211], v[12:15]
	v_mfma_f32_16x16x32_bf16 v[4:7], v[156:159], v[208:211], v[4:7]
	v_mfma_f32_16x16x32_bf16 v[60:63], v[152:155], v[184:187], v[60:63]
	v_mfma_f32_16x16x32_bf16 v[52:55], v[160:163], v[184:187], v[52:55]
	v_mfma_f32_16x16x32_bf16 v[44:47], v[152:155], v[196:199], v[44:47]
	v_mfma_f32_16x16x32_bf16 v[36:39], v[160:163], v[196:199], v[36:39]
	v_mfma_f32_16x16x32_bf16 v[28:31], v[152:155], v[204:207], v[28:31]
	v_mfma_f32_16x16x32_bf16 v[20:23], v[160:163], v[204:207], v[20:23]
	v_mfma_f32_16x16x32_bf16 v[12:15], v[152:155], v[212:215], v[12:15]
	v_mfma_f32_16x16x32_bf16 v[4:7], v[160:163], v[212:215], v[4:7]
	v_mfma_f32_16x16x32_bf16 v[56:59], v[164:167], v[180:183], v[56:59]
	v_mfma_f32_16x16x32_bf16 v[48:51], v[172:175], v[180:183], v[48:51]
	v_mfma_f32_16x16x32_bf16 v[40:43], v[164:167], v[192:195], v[40:43]
	v_mfma_f32_16x16x32_bf16 v[32:35], v[172:175], v[192:195], v[32:35]
	v_mfma_f32_16x16x32_bf16 v[24:27], v[164:167], v[200:203], v[24:27]
	v_mfma_f32_16x16x32_bf16 v[16:19], v[172:175], v[200:203], v[16:19]
	v_mfma_f32_16x16x32_bf16 v[8:11], v[164:167], v[208:211], v[8:11]
	v_mfma_f32_16x16x32_bf16 v[0:3], v[172:175], v[208:211], v[0:3]
	v_mfma_f32_16x16x32_bf16 v[56:59], v[168:171], v[184:187], v[56:59]
	v_mfma_f32_16x16x32_bf16 v[48:51], v[176:179], v[184:187], v[48:51]
	v_mfma_f32_16x16x32_bf16 v[40:43], v[168:171], v[196:199], v[40:43]
	v_mfma_f32_16x16x32_bf16 v[32:35], v[176:179], v[196:199], v[32:35]
	v_mfma_f32_16x16x32_bf16 v[24:27], v[168:171], v[204:207], v[24:27]
	v_mfma_f32_16x16x32_bf16 v[16:19], v[176:179], v[204:207], v[16:19]
	v_mfma_f32_16x16x32_bf16 v[8:11], v[168:171], v[212:215], v[8:11]
	v_mfma_f32_16x16x32_bf16 v[0:3], v[176:179], v[212:215], v[0:3]
	s_barrier
	s_add_i32 s82, s82, 2
	s_add_u32 s62, s62, 0x10000
	s_addc_u32 s63, s63, 0
	s_add_u32 s64, s64, 0x10000
	s_addc_u32 s65, s65, 0
	s_cmp_gt_u32 s82, 13

; __device__ __forceinline__ unsigned cvt_pk_bf16(float lo, float hi) { unsigned r; asm volatile("v_cvt_pk_bf16_f32 %0, %1, %2" : "=v"(r) : "v"(lo), "v"(hi)); return r; }
;     __device__ __forceinline__ void operator()(f32x4 (&acc)[2][2][4][2], const Unit& u, int wr, int wc, int fr, int fq) const {
;         const int row0 = u.pm * BM + wr * 64 + fr, col0 = u.pn * HALF + wc * 32 + 8 * fq;
;         bf16_t* Ob = O + ((size_t)(u.pm * ldc + (col0 >> 6)) * BM) * 64;
;         float sq[2][4];
; #pragma unroll
;         for (int ai = 0; ai < 2; ++ai)
; #pragma unroll
;             for (int m = 0; m < 4; ++m) sq[ai][m] = ssq[row0 + ai * HALF + m * 16];
; #pragma unroll
;         for (int ai = 0; ai < 2; ++ai)
; #pragma unroll
;             for (int m = 0; m < 4; ++m) { const float ms = sq[ai][m] * (1.0f / 1024.0f) + 1e-6f, nrl = -__builtin_amdgcn_rsqf(ms) * LOG2E;
;                 float o[8];
; #pragma unroll
;                 for (int n = 0; n < 2; ++n)
; #pragma unroll
;                     for (int e = 0; e < 4; ++e) { const float a = acc[ai][0][m][n][e], bb = acc[ai][1][m][n][e];
;                         o[4 * n + e] = (a * bb) * __builtin_amdgcn_rcpf(__builtin_fmaf(__builtin_amdgcn_exp2f(a * nrl), ms, ms)); }
;                 u32x4 w; w.x = cvt_pk_bf16(o[0], o[1]); w.y = cvt_pk_bf16(o[2], o[3]); w.z = cvt_pk_bf16(o[4], o[5]); w.w = cvt_pk_bf16(o[6], o[7]);
;                 *(u32x4*)((char*)Ob + ai * HTB + lds_byte(wr * 64 + m * 16 + fr, (col0 & 63))) = w; }
.LBB0_841:
	s_lshl_b32 s53, s61, 7
	s_or_b32 s53, s53, s71
	s_mul_i32 s55, s60, 44
	s_ashr_i32 s53, s53, 6
	s_add_i32 s60, s53, s55
	s_ashr_i32 s61, s60, 31
	s_lshl_b64 s[60:61], s[60:61], 15
	s_add_u32 s60, s28, s60
	s_addc_u32 s61, s29, s61
	v_pk_mul_f32 v[124:125], v[116:117], v[124:125]
	v_pk_mul_f32 v[126:127], v[118:119], v[126:127]
	v_pk_mul_f32 v[120:121], v[112:113], v[120:121]
	v_pk_mul_f32 v[122:123], v[114:115], v[122:123]
	v_pk_mul_f32 v[104:105], v[108:109], v[104:105]
	v_pk_mul_f32 v[106:107], v[110:111], v[106:107]
	v_pk_mul_f32 v[96:97], v[100:101], v[96:97]
	v_pk_mul_f32 v[98:99], v[102:103], v[98:99]
	v_pk_mul_f32 v[88:89], v[92:93], v[88:89]
	v_pk_mul_f32 v[90:91], v[94:95], v[90:91]
	v_pk_mul_f32 v[80:81], v[84:85], v[80:81]
	v_pk_mul_f32 v[82:83], v[86:87], v[82:83]
	v_pk_mul_f32 v[72:73], v[76:77], v[72:73]
	v_pk_mul_f32 v[74:75], v[78:79], v[74:75]
	v_pk_mul_f32 v[64:65], v[68:69], v[64:65]
	v_pk_mul_f32 v[66:67], v[70:71], v[66:67]
	v_pk_mul_f32 v[56:57], v[60:61], v[56:57]
	v_pk_mul_f32 v[58:59], v[62:63], v[58:59]
	v_pk_mul_f32 v[48:49], v[52:53], v[48:49]
	v_pk_mul_f32 v[50:51], v[54:55], v[50:51]
	v_pk_mul_f32 v[40:41], v[44:45], v[40:41]
	v_pk_mul_f32 v[42:43], v[46:47], v[42:43]
	v_pk_mul_f32 v[32:33], v[36:37], v[32:33]
	v_pk_mul_f32 v[34:35], v[38:39], v[34:35]
	v_pk_mul_f32 v[24:25], v[28:29], v[24:25]
	v_pk_mul_f32 v[26:27], v[30:31], v[26:27]
	v_pk_mul_f32 v[16:17], v[20:21], v[16:17]
	v_pk_mul_f32 v[18:19], v[22:23], v[18:19]
	v_pk_mul_f32 v[8:9], v[12:13], v[8:9]
	v_pk_mul_f32 v[10:11], v[14:15], v[10:11]
	v_pk_mul_f32 v[0:1], v[4:5], v[0:1]
	v_pk_mul_f32 v[2:3], v[6:7], v[2:3]
	v_readlane_b32 s99, v246, 6
	s_nop 1
	s_cmp_lt_u32 s99, 4
	s_cbranch_scc0 .Lnoal_6
	s_barrier
.Lnoal_6:
	v_fmamk_f32 v152, v247, 0x3a800000, v146
	v_fmamk_f32 v160, v248, 0x3a800000, v146
	v_fmamk_f32 v162, v249, 0x3a800000, v146
	v_fmamk_f32 v164, v250, 0x3a800000, v146
	v_fmamk_f32 v166, v251, 0x3a800000, v146
	v_fmamk_f32 v168, v252, 0x3a800000, v146
	v_fmamk_f32 v170, v253, 0x3a800000, v146
	v_fmamk_f32 v172, v254, 0x3a800000, v146
	v_rsq_f32_e32 v153, v152
	v_rsq_f32_e32 v161, v160
	v_rsq_f32_e32 v163, v162
	v_rsq_f32_e32 v165, v164
	v_rsq_f32_e32 v167, v166
	v_rsq_f32_e32 v169, v168
	v_rsq_f32_e32 v171, v170
	v_rsq_f32_e32 v173, v172
	v_mul_f32_e32 v153, 0xbfb8aa3b, v153
	v_mul_f32_e32 v161, 0xbfb8aa3b, v161
	v_mul_f32_e32 v163, 0xbfb8aa3b, v163
	v_mul_f32_e32 v165, 0xbfb8aa3b, v165
	v_mul_f32_e32 v167, 0xbfb8aa3b, v167
	v_mul_f32_e32 v169, 0xbfb8aa3b, v169
	v_mul_f32_e32 v171, 0xbfb8aa3b, v171
	v_mul_f32_e32 v173, 0xbfb8aa3b, v173
	v_pk_mul_f32 v[116:117], v[116:117], v[152:153] op_sel:[0,1] op_sel_hi:[1,1]
	v_pk_mul_f32 v[118:119], v[118:119], v[152:153] op_sel:[0,1] op_sel_hi:[1,1]
	v_pk_mul_f32 v[112:113], v[112:113], v[152:153] op_sel:[0,1] op_sel_hi:[1,1]
	v_pk_mul_f32 v[114:115], v[114:115], v[152:153] op_sel:[0,1] op_sel_hi:[1,1]
	v_exp_f32_e32 v116, v116
	v_exp_f32_e32 v117, v117
	v_exp_f32_e32 v118, v118
	v_exp_f32_e32 v119, v119
	v_exp_f32_e32 v112, v112
	v_exp_f32_e32 v113, v113
	v_exp_f32_e32 v114, v114
	v_exp_f32_e32 v115, v115
	v_pk_fma_f32 v[116:117], v[116:117], v[152:153], v[152:153] op_sel_hi:[1,0,0]
	v_pk_fma_f32 v[118:119], v[118:119], v[152:153], v[152:153] op_sel_hi:[1,0,0]
	v_pk_fma_f32 v[112:113], v[112:113], v[152:153], v[152:153] op_sel_hi:[1,0,0]
	v_pk_fma_f32 v[114:115], v[114:115], v[152:153], v[152:153] op_sel_hi:[1,0,0]
	v_rcp_f32_e32 v116, v116
	v_rcp_f32_e32 v117, v117
	v_rcp_f32_e32 v118, v118
	v_rcp_f32_e32 v119, v119
	v_rcp_f32_e32 v112, v112
	v_rcp_f32_e32 v113, v113
	v_rcp_f32_e32 v114, v114
	v_rcp_f32_e32 v115, v115
	v_pk_mul_f32 v[124:125], v[124:125], v[116:117]
	v_pk_mul_f32 v[126:127], v[126:127], v[118:119]
	v_pk_mul_f32 v[120:121], v[120:121], v[112:113]
	v_pk_mul_f32 v[122:123], v[122:123], v[114:115]
	v_cvt_pk_bf16_f32 v208, v124, v125
	v_cvt_pk_bf16_f32 v209, v126, v127
	v_cvt_pk_bf16_f32 v210, v120, v121
	v_cvt_pk_bf16_f32 v211, v122, v123
	v_lshl_add_u64 v[174:175], s[60:61], 0, v[128:129]
	global_store_dwordx4 v[174:175], v[208:211], off sc1
	v_pk_mul_f32 v[108:109], v[108:109], v[160:161] op_sel:[0,1] op_sel_hi:[1,1]
	v_pk_mul_f32 v[110:111], v[110:111], v[160:161] op_sel:[0,1] op_sel_hi:[1,1]
	v_pk_mul_f32 v[100:101], v[100:101], v[160:161] op_sel:[0,1] op_sel_hi:[1,1]
	v_pk_mul_f32 v[102:103], v[102:103], v[160:161] op_sel:[0,1] op_sel_hi:[1,1]
	v_exp_f32_e32 v108, v108
	v_exp_f32_e32 v109, v109
	v_exp_f32_e32 v110, v110
	v_exp_f32_e32 v111, v111
	v_exp_f32_e32 v100, v100
	v_exp_f32_e32 v101, v101
	v_exp_f32_e32 v102, v102
	v_exp_f32_e32 v103, v103
	v_pk_fma_f32 v[108:109], v[108:109], v[160:161], v[160:161] op_sel_hi:[1,0,0]
	v_pk_fma_f32 v[110:111], v[110:111], v[160:161], v[160:161] op_sel_hi:[1,0,0]
	v_pk_fma_f32 v[100:101], v[100:101], v[160:161], v[160:161] op_sel_hi:[1,0,0]
	v_pk_fma_f32 v[102:103], v[102:103], v[160:161], v[160:161] op_sel_hi:[1,0,0]
	v_rcp_f32_e32 v108, v108
	v_rcp_f32_e32 v109, v109
	v_rcp_f32_e32 v110, v110
	v_rcp_f32_e32 v111, v111
	v_rcp_f32_e32 v100, v100
	v_rcp_f32_e32 v101, v101
	v_rcp_f32_e32 v102, v102
	v_rcp_f32_e32 v103, v103
	v_pk_mul_f32 v[104:105], v[104:105], v[108:109]
	v_pk_mul_f32 v[106:107], v[106:107], v[110:111]
	v_pk_mul_f32 v[96:97], v[96:97], v[100:101]
	v_pk_mul_f32 v[98:99], v[98:99], v[102:103]
	v_cvt_pk_bf16_f32 v212, v104, v105
	v_cvt_pk_bf16_f32 v213, v106, v107
	v_cvt_pk_bf16_f32 v214, v96, v97
	v_cvt_pk_bf16_f32 v215, v98, v99
	v_lshl_add_u64 v[174:175], s[60:61], 0, v[130:131]
	global_store_dwordx4 v[174:175], v[212:215], off sc1
	v_pk_mul_f32 v[92:93], v[92:93], v[162:163] op_sel:[0,1] op_sel_hi:[1,1]
; __device__ __forceinline__ unsigned cvt_pk_bf16(float lo, float hi) { unsigned r; asm volatile("v_cvt_pk_bf16_f32 %0, %1, %2" : "=v"(r) : "v"(lo), "v"(hi)); return r; }
;     __device__ __forceinline__ void operator()(f32x4 (&acc)[2][2][4][2], const Unit& u, int wr, int wc, int fr, int fq) const {
;     ...
;         for (int ai = 0; ai < 2; ++ai)
; #pragma unroll
;             for (int m = 0; m < 4; ++m) { const float ms = sq[ai][m] * (1.0f / 1024.0f) + 1e-6f, nrl = -__builtin_amdgcn_rsqf(ms) * LOG2E;
;                 float o[8];
; #pragma unroll
;                 for (int n = 0; n < 2; ++n)
; #pragma unroll
;                     for (int e = 0; e < 4; ++e) { const float a = acc[ai][0][m][n][e], bb = acc[ai][1][m][n][e];
;                         o[4 * n + e] = (a * bb) * __builtin_amdgcn_rcpf(__builtin_fmaf(__builtin_amdgcn_exp2f(a * nrl), ms, ms)); }
;                 u32x4 w; w.x = cvt_pk_bf16(o[0], o[1]); w.y = cvt_pk_bf16(o[2], o[3]); w.z = cvt_pk_bf16(o[4], o[5]); w.w = cvt_pk_bf16(o[6], o[7]);
;                 *(u32x4*)((char*)Ob + ai * HTB + lds_byte(wr * 64 + m * 16 + fr, (col0 & 63))) = w; }
	v_pk_mul_f32 v[94:95], v[94:95], v[162:163] op_sel:[0,1] op_sel_hi:[1,1]
	v_pk_mul_f32 v[84:85], v[84:85], v[162:163] op_sel:[0,1] op_sel_hi:[1,1]
	v_pk_mul_f32 v[86:87], v[86:87], v[162:163] op_sel:[0,1] op_sel_hi:[1,1]
	v_exp_f32_e32 v92, v92
	v_exp_f32_e32 v93, v93
	v_exp_f32_e32 v94, v94
	v_exp_f32_e32 v95, v95
	v_exp_f32_e32 v84, v84
	v_exp_f32_e32 v85, v85
	v_exp_f32_e32 v86, v86
	v_exp_f32_e32 v87, v87
	v_pk_fma_f32 v[92:93], v[92:93], v[162:163], v[162:163] op_sel_hi:[1,0,0]
	v_pk_fma_f32 v[94:95], v[94:95], v[162:163], v[162:163] op_sel_hi:[1,0,0]
	v_pk_fma_f32 v[84:85], v[84:85], v[162:163], v[162:163] op_sel_hi:[1,0,0]
	v_pk_fma_f32 v[86:87], v[86:87], v[162:163], v[162:163] op_sel_hi:[1,0,0]
	v_rcp_f32_e32 v92, v92
	v_rcp_f32_e32 v93, v93
	v_rcp_f32_e32 v94, v94
	v_rcp_f32_e32 v95, v95
	v_rcp_f32_e32 v84, v84
	v_rcp_f32_e32 v85, v85
	v_rcp_f32_e32 v86, v86
	v_rcp_f32_e32 v87, v87
	v_pk_mul_f32 v[88:89], v[88:89], v[92:93]
	v_pk_mul_f32 v[90:91], v[90:91], v[94:95]
	v_pk_mul_f32 v[80:81], v[80:81], v[84:85]
	v_pk_mul_f32 v[82:83], v[82:83], v[86:87]
	v_cvt_pk_bf16_f32 v208, v88, v89
	v_cvt_pk_bf16_f32 v209, v90, v91
	v_cvt_pk_bf16_f32 v210, v80, v81
	v_cvt_pk_bf16_f32 v211, v82, v83
	v_lshl_add_u64 v[174:175], s[60:61], 0, v[132:133]
	global_store_dwordx4 v[174:175], v[208:211], off sc1
	v_pk_mul_f32 v[76:77], v[76:77], v[164:165] op_sel:[0,1] op_sel_hi:[1,1]
	v_pk_mul_f32 v[78:79], v[78:79], v[164:165] op_sel:[0,1] op_sel_hi:[1,1]
	v_pk_mul_f32 v[68:69], v[68:69], v[164:165] op_sel:[0,1] op_sel_hi:[1,1]
	v_pk_mul_f32 v[70:71], v[70:71], v[164:165] op_sel:[0,1] op_sel_hi:[1,1]
	v_exp_f32_e32 v76, v76
	v_exp_f32_e32 v77, v77
	v_exp_f32_e32 v78, v78
	v_exp_f32_e32 v79, v79
	v_exp_f32_e32 v68, v68
	v_exp_f32_e32 v69, v69
	v_exp_f32_e32 v70, v70
	v_exp_f32_e32 v71, v71
	v_pk_fma_f32 v[76:77], v[76:77], v[164:165], v[164:165] op_sel_hi:[1,0,0]
	v_pk_fma_f32 v[78:79], v[78:79], v[164:165], v[164:165] op_sel_hi:[1,0,0]
	v_pk_fma_f32 v[68:69], v[68:69], v[164:165], v[164:165] op_sel_hi:[1,0,0]
	v_pk_fma_f32 v[70:71], v[70:71], v[164:165], v[164:165] op_sel_hi:[1,0,0]
	v_rcp_f32_e32 v76, v76
	v_rcp_f32_e32 v77, v77
	v_rcp_f32_e32 v78, v78
	v_rcp_f32_e32 v79, v79
	v_rcp_f32_e32 v68, v68
	v_rcp_f32_e32 v69, v69
	v_rcp_f32_e32 v70, v70
	v_rcp_f32_e32 v71, v71
	v_pk_mul_f32 v[72:73], v[72:73], v[76:77]
	v_pk_mul_f32 v[74:75], v[74:75], v[78:79]
	v_pk_mul_f32 v[64:65], v[64:65], v[68:69]
	v_pk_mul_f32 v[66:67], v[66:67], v[70:71]
	v_cvt_pk_bf16_f32 v212, v72, v73
	v_cvt_pk_bf16_f32 v213, v74, v75
	v_cvt_pk_bf16_f32 v214, v64, v65
	v_cvt_pk_bf16_f32 v215, v66, v67
	v_lshl_add_u64 v[174:175], s[60:61], 0, v[134:135]
	global_store_dwordx4 v[174:175], v[212:215], off sc1
	s_add_u32 s60, s60, 0x4000
	s_addc_u32 s61, s61, 0
	v_pk_mul_f32 v[60:61], v[60:61], v[166:167] op_sel:[0,1] op_sel_hi:[1,1]
	v_pk_mul_f32 v[62:63], v[62:63], v[166:167] op_sel:[0,1] op_sel_hi:[1,1]
	v_pk_mul_f32 v[52:53], v[52:53], v[166:167] op_sel:[0,1] op_sel_hi:[1,1]
	v_pk_mul_f32 v[54:55], v[54:55], v[166:167] op_sel:[0,1] op_sel_hi:[1,1]
	v_exp_f32_e32 v60, v60
	v_exp_f32_e32 v61, v61
	v_exp_f32_e32 v62, v62
	v_exp_f32_e32 v63, v63
	v_exp_f32_e32 v52, v52
	v_exp_f32_e32 v53, v53
	v_exp_f32_e32 v54, v54
	v_exp_f32_e32 v55, v55
	v_pk_fma_f32 v[60:61], v[60:61], v[166:167], v[166:167] op_sel_hi:[1,0,0]
	v_pk_fma_f32 v[62:63], v[62:63], v[166:167], v[166:167] op_sel_hi:[1,0,0]
	v_pk_fma_f32 v[52:53], v[52:53], v[166:167], v[166:167] op_sel_hi:[1,0,0]
	v_pk_fma_f32 v[54:55], v[54:55], v[166:167], v[166:167] op_sel_hi:[1,0,0]
	v_rcp_f32_e32 v60, v60
	v_rcp_f32_e32 v61, v61
	v_rcp_f32_e32 v62, v62
	v_rcp_f32_e32 v63, v63
	v_rcp_f32_e32 v52, v52
	v_rcp_f32_e32 v53, v53
	v_rcp_f32_e32 v54, v54
	v_rcp_f32_e32 v55, v55
	v_pk_mul_f32 v[56:57], v[56:57], v[60:61]
	v_pk_mul_f32 v[58:59], v[58:59], v[62:63]
	v_pk_mul_f32 v[48:49], v[48:49], v[52:53]
	v_pk_mul_f32 v[50:51], v[50:51], v[54:55]
	v_cvt_pk_bf16_f32 v208, v56, v57
	v_cvt_pk_bf16_f32 v209, v58, v59
	v_cvt_pk_bf16_f32 v210, v48, v49
	v_cvt_pk_bf16_f32 v211, v50, v51
	v_lshl_add_u64 v[174:175], s[60:61], 0, v[128:129]
	global_store_dwordx4 v[174:175], v[208:211], off sc1
	v_pk_mul_f32 v[44:45], v[44:45], v[168:169] op_sel:[0,1] op_sel_hi:[1,1]
; __device__ __forceinline__ unsigned cvt_pk_bf16(float lo, float hi) { unsigned r; asm volatile("v_cvt_pk_bf16_f32 %0, %1, %2" : "=v"(r) : "v"(lo), "v"(hi)); return r; }
; #define PG8_BAR __builtin_amdgcn_s_barrier()
;     __device__ __forceinline__ void operator()(f32x4 (&acc)[2][2][4][2], const Unit& u, int wr, int wc, int fr, int fq) const {
;     ...
;         for (int ai = 0; ai < 2; ++ai)
; #pragma unroll
;             for (int m = 0; m < 4; ++m) { const float ms = sq[ai][m] * (1.0f / 1024.0f) + 1e-6f, nrl = -__builtin_amdgcn_rsqf(ms) * LOG2E;
;                 float o[8];
; #pragma unroll
;                 for (int n = 0; n < 2; ++n)
; #pragma unroll
;                     for (int e = 0; e < 4; ++e) { const float a = acc[ai][0][m][n][e], bb = acc[ai][1][m][n][e];
;                         o[4 * n + e] = (a * bb) * __builtin_amdgcn_rcpf(__builtin_fmaf(__builtin_amdgcn_exp2f(a * nrl), ms, ms)); }
;                 u32x4 w; w.x = cvt_pk_bf16(o[0], o[1]); w.y = cvt_pk_bf16(o[2], o[3]); w.z = cvt_pk_bf16(o[4], o[5]); w.w = cvt_pk_bf16(o[6], o[7]);
;                 *(u32x4*)((char*)Ob + ai * HTB + lds_byte(wr * 64 + m * 16 + fr, (col0 & 63))) = w; }
; template <class Epi, class Sched, bool ALIGN_EPI = false, bool SP2 = false>
; __device__ __forceinline__ void gemm_phase(PG8_LAS unsigned char* lds, const Gemm g, const Sched& S, const Epi& E) {
;     ...
;         if (!has_next) break;
; #pragma unroll
;         for (int a = 0; a < 2; ++a)
; #pragma unroll
;             for (int b = 0; b < 2; ++b)
; #pragma unroll
;                 for (int m = 0; m < 4; ++m)
; #pragma unroll
;                     for (int n = 0; n < 2; ++n) acc[a][b][m][n] = (f32x4){0.f, 0.f, 0.f, 0.f};
;         cur = nxt; cA = nA; cB = nB; ++ui;
;         if constexpr (ALIGN_EPI) { if (wr == 1) PG8_BAR; }
	v_pk_mul_f32 v[46:47], v[46:47], v[168:169] op_sel:[0,1] op_sel_hi:[1,1]
	v_pk_mul_f32 v[36:37], v[36:37], v[168:169] op_sel:[0,1] op_sel_hi:[1,1]
	v_pk_mul_f32 v[38:39], v[38:39], v[168:169] op_sel:[0,1] op_sel_hi:[1,1]
	v_exp_f32_e32 v44, v44
	v_exp_f32_e32 v45, v45
	v_exp_f32_e32 v46, v46
	v_exp_f32_e32 v47, v47
	v_exp_f32_e32 v36, v36
	v_exp_f32_e32 v37, v37
	v_exp_f32_e32 v38, v38
	v_exp_f32_e32 v39, v39
	v_pk_fma_f32 v[44:45], v[44:45], v[168:169], v[168:169] op_sel_hi:[1,0,0]
	v_pk_fma_f32 v[46:47], v[46:47], v[168:169], v[168:169] op_sel_hi:[1,0,0]
	v_pk_fma_f32 v[36:37], v[36:37], v[168:169], v[168:169] op_sel_hi:[1,0,0]
	v_pk_fma_f32 v[38:39], v[38:39], v[168:169], v[168:169] op_sel_hi:[1,0,0]
	v_rcp_f32_e32 v44, v44
	v_rcp_f32_e32 v45, v45
	v_rcp_f32_e32 v46, v46
	v_rcp_f32_e32 v47, v47
	v_rcp_f32_e32 v36, v36
	v_rcp_f32_e32 v37, v37
	v_rcp_f32_e32 v38, v38
	v_rcp_f32_e32 v39, v39
	v_pk_mul_f32 v[40:41], v[40:41], v[44:45]
	v_pk_mul_f32 v[42:43], v[42:43], v[46:47]
	v_pk_mul_f32 v[32:33], v[32:33], v[36:37]
	v_pk_mul_f32 v[34:35], v[34:35], v[38:39]
	v_cvt_pk_bf16_f32 v212, v40, v41
	v_cvt_pk_bf16_f32 v213, v42, v43
	v_cvt_pk_bf16_f32 v214, v32, v33
	v_cvt_pk_bf16_f32 v215, v34, v35
	v_lshl_add_u64 v[174:175], s[60:61], 0, v[130:131]
	global_store_dwordx4 v[174:175], v[212:215], off sc1
	v_pk_mul_f32 v[28:29], v[28:29], v[170:171] op_sel:[0,1] op_sel_hi:[1,1]
	v_pk_mul_f32 v[30:31], v[30:31], v[170:171] op_sel:[0,1] op_sel_hi:[1,1]
	v_pk_mul_f32 v[20:21], v[20:21], v[170:171] op_sel:[0,1] op_sel_hi:[1,1]
	v_pk_mul_f32 v[22:23], v[22:23], v[170:171] op_sel:[0,1] op_sel_hi:[1,1]
	v_exp_f32_e32 v28, v28
	v_exp_f32_e32 v29, v29
	v_exp_f32_e32 v30, v30
	v_exp_f32_e32 v31, v31
	v_exp_f32_e32 v20, v20
	v_exp_f32_e32 v21, v21
	v_exp_f32_e32 v22, v22
	v_exp_f32_e32 v23, v23
	v_pk_fma_f32 v[28:29], v[28:29], v[170:171], v[170:171] op_sel_hi:[1,0,0]
	v_pk_fma_f32 v[30:31], v[30:31], v[170:171], v[170:171] op_sel_hi:[1,0,0]
	v_pk_fma_f32 v[20:21], v[20:21], v[170:171], v[170:171] op_sel_hi:[1,0,0]
	v_pk_fma_f32 v[22:23], v[22:23], v[170:171], v[170:171] op_sel_hi:[1,0,0]
	v_rcp_f32_e32 v28, v28
	v_rcp_f32_e32 v29, v29
	v_rcp_f32_e32 v30, v30
	v_rcp_f32_e32 v31, v31
	v_rcp_f32_e32 v20, v20
	v_rcp_f32_e32 v21, v21
	v_rcp_f32_e32 v22, v22
	v_rcp_f32_e32 v23, v23
	v_pk_mul_f32 v[24:25], v[24:25], v[28:29]
	v_pk_mul_f32 v[26:27], v[26:27], v[30:31]
	v_pk_mul_f32 v[16:17], v[16:17], v[20:21]
	v_pk_mul_f32 v[18:19], v[18:19], v[22:23]
	v_cvt_pk_bf16_f32 v208, v24, v25
	v_cvt_pk_bf16_f32 v209, v26, v27
	v_cvt_pk_bf16_f32 v210, v16, v17
	v_cvt_pk_bf16_f32 v211, v18, v19
	v_lshl_add_u64 v[174:175], s[60:61], 0, v[132:133]
	global_store_dwordx4 v[174:175], v[208:211], off sc1
	v_pk_mul_f32 v[12:13], v[12:13], v[172:173] op_sel:[0,1] op_sel_hi:[1,1]
	v_pk_mul_f32 v[14:15], v[14:15], v[172:173] op_sel:[0,1] op_sel_hi:[1,1]
	v_pk_mul_f32 v[4:5], v[4:5], v[172:173] op_sel:[0,1] op_sel_hi:[1,1]
	v_pk_mul_f32 v[6:7], v[6:7], v[172:173] op_sel:[0,1] op_sel_hi:[1,1]
	v_exp_f32_e32 v12, v12
	v_exp_f32_e32 v13, v13
	v_exp_f32_e32 v14, v14
	v_exp_f32_e32 v15, v15
	v_exp_f32_e32 v4, v4
	v_exp_f32_e32 v5, v5
	v_exp_f32_e32 v6, v6
	v_exp_f32_e32 v7, v7
	v_pk_fma_f32 v[12:13], v[12:13], v[172:173], v[172:173] op_sel_hi:[1,0,0]
	v_pk_fma_f32 v[14:15], v[14:15], v[172:173], v[172:173] op_sel_hi:[1,0,0]
	v_pk_fma_f32 v[4:5], v[4:5], v[172:173], v[172:173] op_sel_hi:[1,0,0]
	v_pk_fma_f32 v[6:7], v[6:7], v[172:173], v[172:173] op_sel_hi:[1,0,0]
	v_rcp_f32_e32 v12, v12
	v_rcp_f32_e32 v13, v13
	v_rcp_f32_e32 v14, v14
	v_rcp_f32_e32 v15, v15
	v_rcp_f32_e32 v4, v4
	v_rcp_f32_e32 v5, v5
	v_rcp_f32_e32 v6, v6
	v_rcp_f32_e32 v7, v7
	v_pk_mul_f32 v[8:9], v[8:9], v[12:13]
	v_pk_mul_f32 v[10:11], v[10:11], v[14:15]
	v_pk_mul_f32 v[0:1], v[0:1], v[4:5]
	v_pk_mul_f32 v[2:3], v[2:3], v[6:7]
	v_cvt_pk_bf16_f32 v212, v8, v9
	v_cvt_pk_bf16_f32 v213, v10, v11
	v_cvt_pk_bf16_f32 v214, v0, v1
	v_cvt_pk_bf16_f32 v215, v2, v3
	v_lshl_add_u64 v[174:175], s[60:61], 0, v[134:135]
	global_store_dwordx4 v[174:175], v[212:215], off sc1
	s_andn2_b64 vcc, exec, s[2:3]
	s_mov_b64 s[2:3], -1
	s_cbranch_vccnz .LBB0_834
	s_andn2_b64 vcc, exec, s[42:43]
	s_cbranch_vccnz .LBB0_833
	s_barrier
	s_branch .LBB0_833

; __global__ void __launch_bounds__(NTHR, 2) mk_fwd(Args args) {
	.amdhsa_kernel _Z6mk_fwd4Args
		.amdhsa_group_segment_fixed_size 0
		.amdhsa_private_segment_fixed_size 0
		.amdhsa_kernarg_size 408
		.amdhsa_user_sgpr_count 2
		.amdhsa_user_sgpr_dispatch_ptr 0
		.amdhsa_user_sgpr_queue_ptr 0
		.amdhsa_user_sgpr_kernarg_segment_ptr 1
		.amdhsa_user_sgpr_dispatch_id 0
		.amdhsa_user_sgpr_kernarg_preload_length 0
		.amdhsa_user_sgpr_kernarg_preload_offset 0
		.amdhsa_user_sgpr_private_segment_size 0
		.amdhsa_uses_dynamic_stack 0
		.amdhsa_enable_private_segment 0
		.amdhsa_system_sgpr_workgroup_id_x 1
		.amdhsa_system_sgpr_workgroup_id_y 0
		.amdhsa_system_sgpr_workgroup_id_z 0
		.amdhsa_system_sgpr_workgroup_info 0
		.amdhsa_system_vgpr_workitem_id 2
		.amdhsa_next_free_vgpr 255
		.amdhsa_next_free_sgpr 102
		.amdhsa_accum_offset 256
		.amdhsa_reserve_vcc 1
		.amdhsa_float_round_mode_32 0
		.amdhsa_float_round_mode_16_64 0
		.amdhsa_float_denorm_mode_32 3
		.amdhsa_float_denorm_mode_16_64 3
		.amdhsa_dx10_clamp 1
		.amdhsa_ieee_mode 1
		.amdhsa_fp16_overflow 0
		.amdhsa_tg_split 0
		.amdhsa_exception_fp_ieee_invalid_op 0
		.amdhsa_exception_fp_denorm_src 0
		.amdhsa_exception_fp_ieee_div_zero 0
		.amdhsa_exception_fp_ieee_overflow 0
		.amdhsa_exception_fp_ieee_underflow 0
		.amdhsa_exception_fp_ieee_inexact 0
		.amdhsa_exception_int_div_zero 0
	.end_amdhsa_kernel

; __global__ void __launch_bounds__(NTHR, 2) mk_fwd(Args args) {
amdhsa.kernels:
  - .agpr_count:     0
    .args:
      - .offset:         0
        .size:           152
        .value_kind:     by_value
      - .offset:         152
        .size:           4
        .value_kind:     hidden_block_count_x
      - .offset:         156
        .size:           4
        .value_kind:     hidden_block_count_y
      - .offset:         160
        .size:           4
        .value_kind:     hidden_block_count_z
      - .offset:         164
        .size:           2
        .value_kind:     hidden_group_size_x
      - .offset:         166
        .size:           2
        .value_kind:     hidden_group_size_y
      - .offset:         168
        .size:           2
        .value_kind:     hidden_group_size_z
      - .offset:         170
        .size:           2
        .value_kind:     hidden_remainder_x
      - .offset:         172
        .size:           2
        .value_kind:     hidden_remainder_y
      - .offset:         174
        .size:           2
        .value_kind:     hidden_remainder_z
      - .offset:         192
        .size:           8
        .value_kind:     hidden_global_offset_x
      - .offset:         200
        .size:           8
        .value_kind:     hidden_global_offset_y
      - .offset:         208
        .size:           8
        .value_kind:     hidden_global_offset_z
      - .offset:         216
        .size:           2
        .value_kind:     hidden_grid_dims
      - .offset:         240
        .size:           8
        .value_kind:     hidden_multigrid_sync_arg
      - .offset:         272
        .size:           4
        .value_kind:     hidden_dynamic_lds_size
    .group_segment_fixed_size: 0
    .kernarg_segment_align: 8
    .kernarg_segment_size: 408
    .language:       OpenCL C
    .language_version:
      - 2
      - 0
    .max_flat_workgroup_size: 512
    .name:           _Z6mk_fwd4Args
    .private_segment_fixed_size: 0
    .sgpr_count:     108
    .sgpr_spill_count: 12
    .symbol:         _Z6mk_fwd4Args.kd
    .uniform_work_group_size: 1
    .uses_dynamic_stack: false
    .vgpr_count:     255
    .vgpr_spill_count: 0
    .wavefront_size: 64
